# g3_dead_dpp_old_init_deleted
# baseline (speedup 1.0000x reference)
; __device__ __forceinline__ float bperm_f(int src_lane, float v) { return __builtin_bit_cast(float, __builtin_amdgcn_ds_bpermute(src_lane << 2, __builtin_bit_cast(int, v))); }
;     __device__ __forceinline__ void operator()(Acc& acc, const Unit& u, int wr, int wc, int fr, int fq) const {
;         const int b = u.pm / UPU, j = u.pm % UPU;
;         const int tbase = 252 * j + 126 * wr - 2 + fr;
;         const int ch0 = 128 * u.pn + 32 * wc + 8 * fq;
;         float chain = 0.f;
;         { const int ln = (fq << 4) | fr; f32x4 pq[8];
; #pragma unroll
;           for (int q = 0; q < 8; ++q) { const int t = tbase + 16 * q; const bool ok = (t >= 0) && (t < SEQ); pq[q] = *(const f32x4*)(ssq + (size_t)(b * SEQ + (ok ? t : 0)) * 16 + 4 * fq); }
; #pragma unroll
;           for (int q = 0; q < 8; ++q) {
;             const int t = tbase + 16 * q; const bool ok = (t >= 0) && (t < SEQ);
;             float sq = (pq[q][0] + pq[q][1]) + (pq[q][2] + pq[q][3]); sq += bperm_f(ln ^ 16, sq); sq += bperm_f(ln ^ 32, sq);
;             const float rs = rsqrtf(sq * (1.0f / DM) + EPS);
; #pragma unroll
;             for (int bj = 0; bj < 2; ++bj)
; #pragma unroll
;                 for (int n = 0; n < 2; ++n)
; #pragma unroll
;                     for (int i = 0; i < 4; ++i) { const float v = acc[q >> 2][bj][q & 3][n][i]; acc[q >> 2][bj][q & 3][n][i] = ok ? v * rs : 0.f; }
;           }
.LBB0_43:
	s_mul_hi_i32 s21, s20, 0x3e0f83e1
	s_lshr_b32 s27, s21, 31
	s_ashr_i32 s21, s21, 3
	s_add_i32 s21, s21, s27
	s_mul_i32 s27, s21, 33
	s_sub_i32 s20, s20, s27
	s_mulk_i32 s20, 0xfc
	v_add_u32_e32 v198, s20, v194
	v_add_u32_e32 v223, 16, v198
	v_cmp_gt_u32_e64 s[56:57], s97, v198
	v_cmp_gt_u32_e64 s[52:53], s97, v223
	s_lshl_b32 s20, s21, 13
	v_cndmask_b32_e64 v132, 0, v198, s[56:57]
	v_cndmask_b32_e64 v136, 0, v223, s[52:53]
	v_add_u32_e32 v132, s20, v132
	v_add_u32_e32 v136, s20, v136
	v_ashrrev_i32_e32 v133, 31, v132
	v_ashrrev_i32_e32 v137, 31, v136
	v_lshlrev_b64 v[132:133], 6, v[132:133]
	v_lshlrev_b64 v[136:137], 6, v[136:137]
	v_lshl_add_u64 v[132:133], v[146:147], 0, v[132:133]
	v_lshl_add_u64 v[136:137], v[146:147], 0, v[136:137]
	flat_load_dwordx4 v[132:135], v[132:133]
	v_add_u32_e32 v227, 32, v198
	flat_load_dwordx4 v[136:139], v[136:137]
	v_add_u32_e32 v226, 48, v198
	v_cmp_gt_u32_e64 s[54:55], s97, v227
	v_add_u32_e32 v225, 64, v198
	v_cmp_gt_u32_e64 s[50:51], s97, v226
	v_cndmask_b32_e64 v152, 0, v227, s[54:55]
	v_cmp_gt_u32_e64 s[48:49], s97, v225
	v_cndmask_b32_e64 v153, 0, v226, s[50:51]
	v_add_u32_e32 v152, s20, v152
	v_cndmask_b32_e64 v155, 0, v225, s[48:49]
	v_add_u32_e32 v154, s20, v153
	v_ashrrev_i32_e32 v153, 31, v152
	v_add_u32_e32 v156, s20, v155
	v_ashrrev_i32_e32 v155, 31, v154
	v_lshlrev_b64 v[152:153], 6, v[152:153]
	v_lshlrev_b64 v[154:155], 6, v[154:155]
	v_add_u32_e32 v224, 0x50, v198
	v_cmp_gt_u32_e64 s[46:47], s97, v224
	s_mov_b32 s44, 0x358637bd
	v_add_u32_e32 v222, 0x60, v198
	v_add_u32_e32 v199, 0x70, v198
	v_cndmask_b32_e64 v157, 0, v224, s[46:47]
	v_mov_b64_e32 v[188:189], s[44:45]
	v_cmp_gt_u32_e64 s[44:45], s97, v222
	v_cmp_gt_u32_e32 vcc, s97, v199
	v_add_u32_e32 v158, s20, v157
	v_ashrrev_i32_e32 v157, 31, v156
	v_cndmask_b32_e64 v159, 0, v222, s[44:45]
	v_cndmask_b32_e32 v161, 0, v199, vcc
	v_lshlrev_b64 v[156:157], 6, v[156:157]
	s_mov_b32 s90, 0x3a800000
	v_add_u32_e32 v160, s20, v159
	v_add_u32_e32 v162, s20, v161
	v_ashrrev_i32_e32 v159, 31, v158
	v_ashrrev_i32_e32 v161, 31, v160
	v_ashrrev_i32_e32 v163, 31, v162
	v_lshlrev_b64 v[158:159], 6, v[158:159]
	v_lshlrev_b64 v[160:161], 6, v[160:161]
	v_lshlrev_b64 v[162:163], 6, v[162:163]
	s_waitcnt vmcnt(0) lgkmcnt(0)
	v_mov_b32_e32 v174, v133
	v_mov_b32_e32 v175, v134
	v_mov_b32_e32 v133, v135
	v_mov_b32_e32 v134, v137
	v_mov_b32_e32 v135, v138
	v_mov_b32_e32 v137, v139
	v_pk_add_f32 v[132:133], v[174:175], v[132:133]
	v_pk_add_f32 v[134:135], v[134:135], v[136:137]
	v_mov_b32_e32 v137, v132
	v_mov_b32_e32 v136, v134
	v_mov_b32_e32 v132, v135
	v_pk_add_f32 v[132:133], v[136:137], v[132:133]
	v_lshl_add_u64 v[136:137], v[146:147], 0, v[152:153]
	v_lshl_add_u64 v[138:139], v[146:147], 0, v[154:155]
	flat_load_dwordx4 v[190:193], v[136:137]
	flat_load_dwordx4 v[228:231], v[138:139]
	ds_bpermute_b32 v135, v195, v133
	ds_bpermute_b32 v134, v195, v132
	v_lshl_add_u64 v[136:137], v[146:147], 0, v[156:157]
	v_lshl_add_u64 v[138:139], v[146:147], 0, v[158:159]
	v_lshl_add_u64 v[152:153], v[146:147], 0, v[160:161]
	v_lshl_add_u64 v[154:155], v[146:147], 0, v[162:163]
	s_waitcnt lgkmcnt(0)
	v_pk_add_f32 v[132:133], v[132:133], v[134:135]
	ds_bpermute_b32 v135, v196, v133
	ds_bpermute_b32 v134, v196, v132
	s_waitcnt lgkmcnt(0)
	v_pk_add_f32 v[132:133], v[132:133], v[134:135]
	s_nop 0
	v_pk_fma_f32 v[156:157], v[132:133], s[90:91], v[188:189] op_sel_hi:[1,0,0]
	s_nop 0
	v_mul_f32_e32 v132, 0x4b800000, v157
	v_cmp_gt_f32_e64 s[58:59], s29, v157
	s_nop 1
	v_cndmask_b32_e64 v132, v157, v132, s[58:59]
	v_rsq_f32_e32 v157, v132
	flat_load_dwordx4 v[232:235], v[136:137]
	flat_load_dwordx4 v[236:239], v[138:139]
	s_nop 0
	flat_load_dwordx4 v[136:139], v[152:153]
	flat_load_dwordx4 v[132:135], v[154:155]
	v_mul_f32_e32 v152, 0x45800000, v157
	v_cndmask_b32_e64 v153, v157, v152, s[58:59]
	v_mul_f32_e32 v152, v126, v153
	v_mul_f32_e32 v108, v108, v153
	v_mul_f32_e32 v157, v122, v153
	v_cndmask_b32_e64 v122, 0, v152, s[56:57]
	v_cndmask_b32_e64 v152, 0, v108, s[56:57]
	v_mul_f32_e32 v108, v109, v153
	v_mul_f32_e32 v109, 0x4b800000, v156
	v_cmp_gt_f32_e64 s[58:59], s29, v156
	v_mul_f32_e32 v128, v128, v153
	v_mul_f32_e32 v130, v130, v153
	v_cndmask_b32_e64 v109, v156, v109, s[58:59]
	v_rsq_f32_e32 v109, v109
	v_mul_f32_e32 v124, v124, v153
	v_cndmask_b32_e64 v182, 0, v128, s[56:57]
	v_cndmask_b32_e64 v128, 0, v108, s[56:57]
	v_mul_f32_e32 v108, v110, v153
	v_cndmask_b32_e64 v160, 0, v130, s[56:57]
	v_cndmask_b32_e64 v130, 0, v124, s[56:57]
	v_cndmask_b32_e64 v124, 0, v108, s[56:57]
	v_mul_f32_e32 v108, v111, v153
	v_cndmask_b32_e64 v110, 0, v108, s[56:57]
	v_mul_f32_e32 v108, 0x45800000, v109
	v_cndmask_b32_e64 v108, v109, v108, s[58:59]
	v_mul_f32_e32 v109, v116, v108
	v_cndmask_b32_e64 v187, 0, v109, s[52:53]
	v_mul_f32_e32 v109, v117, v108
	v_cndmask_b32_e64 v181, 0, v109, s[52:53]
	v_mul_f32_e32 v109, v118, v108
	v_cndmask_b32_e64 v175, 0, v109, s[52:53]
	v_mul_f32_e32 v109, v119, v108
	v_cndmask_b32_e64 v162, 0, v157, s[56:57]
	v_cndmask_b32_e64 v157, 0, v109, s[52:53]
	v_mul_f32_e32 v109, v112, v108
	v_cndmask_b32_e64 v119, 0, v109, s[52:53]
	v_mul_f32_e32 v109, v113, v108
	v_mul_f32_e32 v104, v104, v108
	v_cndmask_b32_e64 v117, 0, v109, s[52:53]
	v_mul_f32_e32 v109, v114, v108
	v_cndmask_b32_e64 v186, 0, v104, s[52:53]
	v_mul_f32_e32 v104, v105, v108
	v_cndmask_b32_e64 v113, 0, v109, s[52:53]
	v_mul_f32_e32 v109, v115, v108
	v_cndmask_b32_e64 v180, 0, v104, s[52:53]
	v_mul_f32_e32 v106, v106, v108
	v_cndmask_b32_e64 v174, 0, v106, s[52:53]
	v_mul_f32_e32 v106, v107, v108
	v_cndmask_b32_e64 v156, 0, v106, s[52:53]
	v_mul_f32_e32 v92, v92, v108
	v_cndmask_b32_e64 v118, 0, v92, s[52:53]
	v_mul_f32_e32 v92, v93, v108
	v_mul_f32_e32 v121, v121, v153
	s_waitcnt vmcnt(0)
; __device__ __forceinline__ float bperm_f(int src_lane, float v) { return __builtin_bit_cast(float, __builtin_amdgcn_ds_bpermute(src_lane << 2, __builtin_bit_cast(int, v))); }
;     __device__ __forceinline__ void operator()(Acc& acc, const Unit& u, int wr, int wc, int fr, int fq) const {
;     ...
;         { const int ln = (fq << 4) | fr; f32x4 pq[8];
; #pragma unroll
;           for (int q = 0; q < 8; ++q) { const int t = tbase + 16 * q; const bool ok = (t >= 0) && (t < SEQ); pq[q] = *(const f32x4*)(ssq + (size_t)(b * SEQ + (ok ? t : 0)) * 16 + 4 * fq); }
; #pragma unroll
;           for (int q = 0; q < 8; ++q) {
;             const int t = tbase + 16 * q; const bool ok = (t >= 0) && (t < SEQ);
;             float sq = (pq[q][0] + pq[q][1]) + (pq[q][2] + pq[q][3]); sq += bperm_f(ln ^ 16, sq); sq += bperm_f(ln ^ 32, sq);
;             const float rs = rsqrtf(sq * (1.0f / DM) + EPS);
; #pragma unroll
;             for (int bj = 0; bj < 2; ++bj)
; #pragma unroll
;                 for (int n = 0; n < 2; ++n)
; #pragma unroll
;                     for (int i = 0; i < 4; ++i) { const float v = acc[q >> 2][bj][q & 3][n][i]; acc[q >> 2][bj][q & 3][n][i] = ok ? v * rs : 0.f; }
;           }
	v_mov_b32_e32 v104, v191
	v_mov_b32_e32 v105, v192
	v_mov_b32_e32 v191, v193
	v_mov_b32_e32 v114, v229
	v_mov_b32_e32 v115, v230
	v_mov_b32_e32 v229, v231
	v_pk_add_f32 v[104:105], v[104:105], v[190:191]
	v_pk_add_f32 v[114:115], v[114:115], v[228:229]
	v_mov_b32_e32 v191, v104
	v_mov_b32_e32 v190, v114
	v_mov_b32_e32 v104, v115
	v_pk_add_f32 v[104:105], v[190:191], v[104:105]
	ds_bpermute_b32 v115, v195, v105
	ds_bpermute_b32 v114, v195, v104
	v_cndmask_b32_e64 v116, 0, v92, s[52:53]
	v_mul_f32_e32 v129, v129, v153
	v_mul_f32_e32 v131, v131, v153
	v_mul_f32_e32 v125, v125, v153
	s_waitcnt lgkmcnt(0)
	v_pk_add_f32 v[104:105], v[104:105], v[114:115]
	ds_bpermute_b32 v107, v196, v105
	ds_bpermute_b32 v106, v196, v104
	v_mul_f32_e32 v127, v127, v153
	v_mul_f32_e32 v155, v120, v153
	v_cndmask_b32_e64 v178, 0, v121, s[56:57]
	v_mul_f32_e32 v121, v123, v153
	s_waitcnt lgkmcnt(0)
	v_pk_add_f32 v[92:93], v[104:105], v[106:107]
	v_cndmask_b32_e64 v176, 0, v129, s[56:57]
	v_pk_fma_f32 v[92:93], v[92:93], s[90:91], v[188:189] op_sel_hi:[1,0,0]
	v_cndmask_b32_e64 v154, 0, v131, s[56:57]
	v_cndmask_b32_e64 v126, 0, v125, s[56:57]
	v_cndmask_b32_e64 v120, 0, v127, s[56:57]
	v_cndmask_b32_e64 v184, 0, v155, s[56:57]
	v_cndmask_b32_e64 v158, 0, v121, s[56:57]
	v_mul_f32_e32 v104, 0x4b800000, v93
	v_cmp_gt_f32_e64 s[56:57], s29, v93
	v_mul_f32_e32 v94, v94, v108
	v_cndmask_b32_e64 v112, 0, v94, s[52:53]
	v_cndmask_b32_e64 v93, v93, v104, s[56:57]
	v_rsq_f32_e32 v93, v93
	v_mul_f32_e32 v94, v95, v108
	v_cndmask_b32_e64 v108, 0, v94, s[52:53]
	v_cndmask_b32_e64 v109, 0, v109, s[52:53]
	v_mul_f32_e32 v94, 0x45800000, v93
	v_cndmask_b32_e64 v111, v93, v94, s[56:57]
	v_mul_f32_e32 v76, v76, v111
	v_mul_f32_e32 v93, v100, v111
	v_cndmask_b32_e64 v100, 0, v76, s[54:55]
	v_mul_f32_e32 v76, v77, v111
	v_mul_f32_e32 v77, 0x4b800000, v92
	v_cmp_gt_f32_e64 s[52:53], s29, v92
	v_cndmask_b32_e64 v115, 0, v93, s[54:55]
	v_mul_f32_e32 v93, v101, v111
	v_cndmask_b32_e64 v77, v92, v77, s[52:53]
	v_cndmask_b32_e64 v107, 0, v93, s[54:55]
	v_mul_f32_e32 v93, v102, v111
	v_rsq_f32_e32 v77, v77
	v_cndmask_b32_e64 v105, 0, v93, s[54:55]
	v_mul_f32_e32 v93, v103, v111
	v_cndmask_b32_e64 v103, 0, v93, s[54:55]
	v_mul_f32_e32 v93, v96, v111
	v_cndmask_b32_e64 v96, 0, v76, s[54:55]
	v_mul_f32_e32 v76, v78, v111
	v_cndmask_b32_e64 v94, 0, v76, s[54:55]
	v_mul_f32_e32 v76, v79, v111
	v_cndmask_b32_e64 v92, 0, v76, s[54:55]
	v_mul_f32_e32 v76, 0x45800000, v77
	v_cndmask_b32_e64 v101, 0, v93, s[54:55]
	v_mul_f32_e32 v93, v97, v111
	v_mul_f32_e32 v88, v88, v111
	v_cndmask_b32_e64 v76, v77, v76, s[52:53]
	v_cndmask_b32_e64 v97, 0, v93, s[54:55]
	v_mul_f32_e32 v93, v98, v111
	v_cndmask_b32_e64 v114, 0, v88, s[54:55]
	v_mul_f32_e32 v88, v89, v111
	v_mul_f32_e32 v77, v84, v76
	v_cndmask_b32_e64 v95, 0, v93, s[54:55]
	v_mul_f32_e32 v93, v99, v111
	v_cndmask_b32_e64 v106, 0, v88, s[54:55]
	v_mul_f32_e32 v88, v90, v111
	v_cndmask_b32_e64 v99, 0, v77, s[50:51]
	v_mul_f32_e32 v77, v85, v76
	v_cndmask_b32_e64 v104, 0, v88, s[54:55]
	v_mul_f32_e32 v88, v91, v111
	v_cndmask_b32_e64 v91, 0, v77, s[50:51]
	v_mul_f32_e32 v77, v86, v76
	v_cndmask_b32_e64 v89, 0, v77, s[50:51]
	v_mul_f32_e32 v77, v87, v76
	v_cndmask_b32_e64 v87, 0, v77, s[50:51]
	v_mul_f32_e32 v77, v80, v76
	v_cndmask_b32_e64 v85, 0, v77, s[50:51]
	v_mul_f32_e32 v77, v81, v76
	v_mul_f32_e32 v72, v72, v76
	v_cndmask_b32_e64 v81, 0, v77, s[50:51]
	v_mul_f32_e32 v77, v82, v76
	v_cndmask_b32_e64 v98, 0, v72, s[50:51]
	v_mul_f32_e32 v72, v73, v76
	v_cndmask_b32_e64 v79, 0, v77, s[50:51]
	v_mul_f32_e32 v77, v83, v76
	v_cndmask_b32_e64 v90, 0, v72, s[50:51]
	v_mov_b32_e32 v72, v233
	v_mov_b32_e32 v73, v234
	v_mov_b32_e32 v233, v235
	v_mov_b32_e32 v82, v237
	v_mov_b32_e32 v83, v238
	v_mov_b32_e32 v237, v239
	v_pk_add_f32 v[72:73], v[72:73], v[232:233]
	v_pk_add_f32 v[82:83], v[82:83], v[236:237]
	v_mov_b32_e32 v191, v72
	v_mov_b32_e32 v190, v82
	v_mov_b32_e32 v72, v83
	v_pk_add_f32 v[72:73], v[190:191], v[72:73]
	ds_bpermute_b32 v83, v195, v73
	ds_bpermute_b32 v82, v195, v72
	v_mul_f32_e32 v74, v74, v76
	v_cndmask_b32_e64 v102, 0, v88, s[54:55]
	v_cndmask_b32_e64 v88, 0, v74, s[50:51]
	v_mul_f32_e32 v74, v75, v76
	s_waitcnt lgkmcnt(0)
	v_pk_add_f32 v[72:73], v[72:73], v[82:83]
	v_cndmask_b32_e64 v86, 0, v74, s[50:51]
	ds_bpermute_b32 v75, v196, v73
	ds_bpermute_b32 v74, v196, v72
	v_mul_f32_e32 v68, v68, v76
	v_cndmask_b32_e64 v84, 0, v68, s[50:51]
	v_mul_f32_e32 v68, v69, v76
	v_cndmask_b32_e64 v80, 0, v68, s[50:51]
	s_waitcnt lgkmcnt(0)
; __device__ __forceinline__ float bperm_f(int src_lane, float v) { return __builtin_bit_cast(float, __builtin_amdgcn_ds_bpermute(src_lane << 2, __builtin_bit_cast(int, v))); }
;     __device__ __forceinline__ void operator()(Acc& acc, const Unit& u, int wr, int wc, int fr, int fq) const {
;     ...
;         { const int ln = (fq << 4) | fr; f32x4 pq[8];
; #pragma unroll
;           for (int q = 0; q < 8; ++q) { const int t = tbase + 16 * q; const bool ok = (t >= 0) && (t < SEQ); pq[q] = *(const f32x4*)(ssq + (size_t)(b * SEQ + (ok ? t : 0)) * 16 + 4 * fq); }
; #pragma unroll
;           for (int q = 0; q < 8; ++q) {
;             const int t = tbase + 16 * q; const bool ok = (t >= 0) && (t < SEQ);
;             float sq = (pq[q][0] + pq[q][1]) + (pq[q][2] + pq[q][3]); sq += bperm_f(ln ^ 16, sq); sq += bperm_f(ln ^ 32, sq);
;             const float rs = rsqrtf(sq * (1.0f / DM) + EPS);
; #pragma unroll
;             for (int bj = 0; bj < 2; ++bj)
; #pragma unroll
;                 for (int n = 0; n < 2; ++n)
; #pragma unroll
;                     for (int i = 0; i < 4; ++i) { const float v = acc[q >> 2][bj][q & 3][n][i]; acc[q >> 2][bj][q & 3][n][i] = ok ? v * rs : 0.f; }
;           }
	v_pk_add_f32 v[68:69], v[72:73], v[74:75]
	v_mul_f32_e32 v70, v70, v76
	v_pk_fma_f32 v[82:83], v[68:69], s[90:91], v[188:189] op_sel_hi:[1,0,0]
	v_mul_f32_e32 v69, v71, v76
	v_mul_f32_e32 v68, 0x4b800000, v83
	v_cmp_gt_f32_e64 s[52:53], s29, v83
	v_cndmask_b32_e64 v76, 0, v69, s[50:51]
	v_cndmask_b32_e64 v77, 0, v77, s[50:51]
	v_cndmask_b32_e64 v68, v83, v68, s[52:53]
	v_rsq_f32_e32 v68, v68
	v_cndmask_b32_e64 v78, 0, v70, s[50:51]
	v_cmp_gt_f32_e64 s[50:51], s29, v82
	v_cndmask_b32_e64 v93, 0, v93, s[54:55]
	v_mul_f32_e32 v69, 0x45800000, v68
	v_cndmask_b32_e64 v83, v68, v69, s[52:53]
	v_mul_f32_e32 v44, v44, v83
	v_cndmask_b32_e64 v68, 0, v44, s[48:49]
	v_mul_f32_e32 v44, v45, v83
	v_mul_f32_e32 v45, 0x4b800000, v82
	v_mul_f32_e32 v64, v64, v83
	v_cndmask_b32_e64 v45, v82, v45, s[50:51]
	v_cndmask_b32_e64 v191, 0, v64, s[48:49]
	v_mul_f32_e32 v64, v65, v83
	v_mul_f32_e32 v60, v60, v83
	v_rsq_f32_e32 v45, v45
	v_cndmask_b32_e64 v75, 0, v64, s[48:49]
	v_mul_f32_e32 v64, v66, v83
	v_cndmask_b32_e64 v69, 0, v60, s[48:49]
	v_mul_f32_e32 v60, v61, v83
	v_cndmask_b32_e64 v73, 0, v64, s[48:49]
	v_mul_f32_e32 v64, v67, v83
	v_cndmask_b32_e64 v67, 0, v60, s[48:49]
	v_mul_f32_e32 v60, v62, v83
	v_cndmask_b32_e64 v66, 0, v44, s[48:49]
	v_mul_f32_e32 v44, v46, v83
	v_cndmask_b32_e64 v71, 0, v64, s[48:49]
	v_cndmask_b32_e64 v65, 0, v60, s[48:49]
	v_mul_f32_e32 v60, v63, v83
	v_cndmask_b32_e64 v64, 0, v44, s[48:49]
	v_mul_f32_e32 v44, v47, v83
	v_cndmask_b32_e64 v61, 0, v60, s[48:49]
	v_cndmask_b32_e64 v60, 0, v44, s[48:49]
	v_mul_f32_e32 v44, 0x45800000, v45
	v_mul_f32_e32 v56, v56, v83
	v_cndmask_b32_e64 v44, v45, v44, s[50:51]
	v_cndmask_b32_e64 v190, 0, v56, s[48:49]
	v_mul_f32_e32 v56, v57, v83
	v_mul_f32_e32 v45, v52, v44
	v_cndmask_b32_e64 v74, 0, v56, s[48:49]
	v_mul_f32_e32 v56, v58, v83
	v_cndmask_b32_e64 v193, 0, v45, s[46:47]
	v_mul_f32_e32 v45, v53, v44
	v_cndmask_b32_e64 v72, 0, v56, s[48:49]
	v_mul_f32_e32 v56, v59, v83
	v_cndmask_b32_e64 v59, 0, v45, s[46:47]
	v_mul_f32_e32 v45, v54, v44
	v_cndmask_b32_e64 v57, 0, v45, s[46:47]
	v_mul_f32_e32 v45, v55, v44
	v_cndmask_b32_e64 v55, 0, v45, s[46:47]
	v_mul_f32_e32 v45, v48, v44
	v_cndmask_b32_e64 v53, 0, v45, s[46:47]
	v_mul_f32_e32 v45, v49, v44
	v_mul_f32_e32 v40, v40, v44
	v_cndmask_b32_e64 v49, 0, v45, s[46:47]
	v_mul_f32_e32 v45, v50, v44
	v_cndmask_b32_e64 v192, 0, v40, s[46:47]
	v_mul_f32_e32 v40, v41, v44
	v_cndmask_b32_e64 v47, 0, v45, s[46:47]
	v_mul_f32_e32 v45, v51, v44
	v_cndmask_b32_e64 v58, 0, v40, s[46:47]
	v_mov_b32_e32 v40, v137
	v_mov_b32_e32 v41, v138
	v_mov_b32_e32 v137, v139
	v_mov_b32_e32 v50, v133
	v_mov_b32_e32 v51, v134
	v_mov_b32_e32 v133, v135
	v_pk_add_f32 v[40:41], v[40:41], v[136:137]
	v_pk_add_f32 v[50:51], v[50:51], v[132:133]
	v_mov_b32_e32 v63, v40
	v_mov_b32_e32 v62, v50
	v_mov_b32_e32 v40, v51
	v_pk_add_f32 v[40:41], v[62:63], v[40:41]
	ds_bpermute_b32 v51, v195, v41
	ds_bpermute_b32 v50, v195, v40
	v_mul_f32_e32 v42, v42, v44
	v_cndmask_b32_e64 v70, 0, v56, s[48:49]
	v_cndmask_b32_e64 v56, 0, v42, s[46:47]
	v_mul_f32_e32 v42, v43, v44
	s_waitcnt lgkmcnt(0)
	v_pk_add_f32 v[40:41], v[40:41], v[50:51]
	v_cndmask_b32_e64 v54, 0, v42, s[46:47]
	ds_bpermute_b32 v43, v196, v41
	ds_bpermute_b32 v42, v196, v40
	v_mul_f32_e32 v28, v28, v44
	v_cndmask_b32_e64 v52, 0, v28, s[46:47]
	v_mul_f32_e32 v28, v29, v44
	v_cndmask_b32_e64 v48, 0, v28, s[46:47]
	s_waitcnt lgkmcnt(0)
	v_pk_add_f32 v[28:29], v[40:41], v[42:43]
	v_mul_f32_e32 v30, v30, v44
	v_pk_fma_f32 v[28:29], v[28:29], s[90:91], v[188:189] op_sel_hi:[1,0,0]
	v_cndmask_b32_e64 v46, 0, v30, s[46:47]
	v_mul_f32_e32 v40, 0x4b800000, v29
	v_cmp_gt_f32_e64 s[48:49], s29, v29
	v_mul_f32_e32 v30, v31, v44
	v_cndmask_b32_e64 v44, 0, v30, s[46:47]
	v_cndmask_b32_e64 v29, v29, v40, s[48:49]
	v_rsq_f32_e32 v29, v29
	v_cndmask_b32_e64 v45, 0, v45, s[46:47]
	v_cmp_gt_f32_e64 s[46:47], s29, v28
	v_mul_f32_e32 v30, 0x45800000, v29
	v_cndmask_b32_e64 v40, v29, v30, s[48:49]
	v_mul_f32_e32 v12, v12, v40
	v_mul_f32_e32 v29, v36, v40
	v_cndmask_b32_e64 v36, 0, v12, s[44:45]
	v_mul_f32_e32 v12, v13, v40
	v_mul_f32_e32 v13, 0x4b800000, v28
	v_cndmask_b32_e64 v133, 0, v29, s[44:45]
	v_mul_f32_e32 v29, v37, v40
	v_cndmask_b32_e64 v13, v28, v13, s[46:47]
	v_cndmask_b32_e64 v63, 0, v29, s[44:45]
	v_mul_f32_e32 v29, v38, v40
	v_rsq_f32_e32 v13, v13
	v_cndmask_b32_e64 v43, 0, v29, s[44:45]
	v_mul_f32_e32 v29, v39, v40
	v_cndmask_b32_e64 v39, 0, v29, s[44:45]
	v_mul_f32_e32 v29, v32, v40
	v_cndmask_b32_e64 v32, 0, v12, s[44:45]
	v_mul_f32_e32 v12, v14, v40
	v_cndmask_b32_e64 v30, 0, v12, s[44:45]
	v_mul_f32_e32 v12, v15, v40
	v_cndmask_b32_e64 v28, 0, v12, s[44:45]
	v_mul_f32_e32 v12, 0x45800000, v13
	v_cndmask_b32_e64 v12, v13, v12, s[46:47]
	v_mul_f32_e32 v13, v20, v12
	v_cndmask_b32_e32 v135, 0, v13, vcc
	v_mul_f32_e32 v13, v21, v12
	v_cndmask_b32_e32 v83, 0, v13, vcc
	v_mul_f32_e32 v13, v22, v12
	v_cndmask_b32_e64 v37, 0, v29, s[44:45]
	v_mul_f32_e32 v29, v33, v40
	v_mul_f32_e32 v24, v24, v40
	v_cndmask_b32_e32 v51, 0, v13, vcc
	v_mul_f32_e32 v13, v23, v12
	v_cndmask_b32_e64 v33, 0, v29, s[44:45]
	v_mul_f32_e32 v29, v34, v40
	v_cndmask_b32_e64 v132, 0, v24, s[44:45]
	v_mul_f32_e32 v24, v25, v40
	v_cndmask_b32_e32 v41, 0, v13, vcc
	v_mul_f32_e32 v13, v16, v12
	v_mul_f32_e32 v8, v8, v12
	v_mul_f32_e32 v4, v4, v12
	v_cndmask_b32_e64 v31, 0, v29, s[44:45]
	v_mul_f32_e32 v29, v35, v40
	v_cndmask_b32_e64 v62, 0, v24, s[44:45]
	v_mul_f32_e32 v24, v26, v40
	v_cndmask_b32_e32 v35, 0, v13, vcc
	v_mul_f32_e32 v13, v17, v12
	v_cndmask_b32_e32 v134, 0, v8, vcc
	v_mul_f32_e32 v8, v9, v12
	v_cndmask_b32_e32 v34, 0, v4, vcc
	v_mul_f32_e32 v4, v5, v12
; __device__ __forceinline__ float sigmoidf_(float x) { return __builtin_amdgcn_rcpf(1.0f + __expf(-x)); }
; template <int N> __device__ __forceinline__ float dpp_ror(float v) { return __builtin_bit_cast(float, __builtin_amdgcn_update_dpp(0, __builtin_bit_cast(int, v), 0x120 + N, 0xf, 0xf, false)); }
;     __device__ __forceinline__ void operator()(Acc& acc, const Unit& u, int wr, int wc, int fr, int fq) const {
;     ...
;                     for (int i = 0; i < 4; ++i) { const float v = acc[q >> 2][bj][q & 3][n][i]; acc[q >> 2][bj][q & 3][n][i] = ok ? v * rs : 0.f; }
;           }
;           __builtin_amdgcn_sched_barrier(0);
;         }
; #pragma unroll
;         for (int n = 0; n < 2; ++n) {
; #pragma unroll
;             for (int i = 0; i < 4; ++i) {
;                 const int cg_ = ch0 + 4 * n + i, cv_ = DFF + cg_;
;                 const float g0 = cw[cg_], g1 = cw[NUP + cg_], g2 = cw[2 * NUP + cg_], gb = cb[cg_];
;                 const float v0 = cw[cv_], v1 = cw[NUP + cv_], v2 = cw[2 * NUP + cv_], vb = cb[cv_];
;                 float pg1 = 0.f, pg2 = 0.f, pv1 = 0.f, pv2 = 0.f;
; #pragma unroll
;                 for (int q = 0; q < 8; ++q) {
;                     float cgv = acc[q >> 2][0][q & 3][n][i], cvv = acc[q >> 2][1][q & 3][n][i];
;                     asm volatile("" : "+v"(cgv), "+v"(cvv) : "v"(chain));
;                     const float tg1 = dpp_ror<1>(cgv), tg2 = dpp_ror<2>(cgv), tv1 = dpp_ror<1>(cvv), tv2 = dpp_ror<2>(cvv);
;                     const float sg1 = fr >= 1 ? tg1 : pg1, sg2 = fr >= 2 ? tg2 : pg2, sv1 = fr >= 1 ? tv1 : pv1, sv2 = fr >= 2 ? tv2 : pv2;
;                     const float gg = gb + g0 * sg2 + g1 * sg1 + g2 * cgv;
;                     const float vv = vb + v0 * sv2 + v1 * sv1 + v2 * cvv;
;                     chain = gg * sigmoidf_(gg) * vv; acc[q >> 2][0][q & 3][n][i] = chain;
;                     pg1 = tg1; pg2 = tg2; pv1 = tv1; pv2 = tv2;
;                 }
	v_cndmask_b32_e64 v42, 0, v24, s[44:45]
	v_mul_f32_e32 v24, v27, v40
	v_cndmask_b32_e32 v27, 0, v13, vcc
	v_mul_f32_e32 v13, v18, v12
	v_cndmask_b32_e32 v82, 0, v8, vcc
	v_mul_f32_e32 v8, v10, v12
	v_cndmask_b32_e32 v26, 0, v4, vcc
	v_mul_f32_e32 v4, v6, v12
	v_cndmask_b32_e32 v15, 0, v13, vcc
	v_mul_f32_e32 v13, v19, v12
	v_cndmask_b32_e32 v50, 0, v8, vcc
	v_mul_f32_e32 v8, v11, v12
	v_cndmask_b32_e32 v14, 0, v4, vcc
	v_mul_f32_e32 v4, v7, v12
	v_cndmask_b32_e64 v29, 0, v29, s[44:45]
	v_cndmask_b32_e64 v38, 0, v24, s[44:45]
	v_cndmask_b32_e32 v13, 0, v13, vcc
	v_cndmask_b32_e32 v40, 0, v8, vcc
	v_cndmask_b32_e32 v12, 0, v4, vcc
	v_lshl_or_b32 v4, s34, 7, v2
	v_ashrrev_i32_e32 v5, 31, v4
	v_lshlrev_b64 v[16:17], 2, v[4:5]
	v_lshl_add_u64 v[6:7], s[36:37], 0, v[16:17]
	s_movk_i32 s21, 0x5000
	v_add_co_u32_e32 v8, vcc, s21, v6
	s_mov_b32 s21, 0xb000
	s_nop 0
	v_addc_co_u32_e32 v9, vcc, 0, v7, vcc
	v_add_co_u32_e32 v10, vcc, s21, v6
	v_lshl_add_u64 v[16:17], s[60:61], 0, v[16:17]
	s_nop 0
	v_addc_co_u32_e32 v11, vcc, 0, v7, vcc
	global_load_dword v139, v[6:7], off
	global_load_dword v137, v[8:9], off offset:2048
	global_load_dword v136, v[10:11], off
	global_load_dword v189, v[16:17], off
	v_add_co_u32_e32 v18, vcc, s97, v6
	s_mov_b32 s21, 0xd000
	s_nop 0
	v_addc_co_u32_e32 v19, vcc, 0, v7, vcc
	v_add_co_u32_e32 v22, vcc, s80, v6
	global_load_dword v138, v[18:19], off offset:3072
	s_nop 0
	v_addc_co_u32_e32 v23, vcc, 0, v7, vcc
	v_add_co_u32_e32 v20, vcc, s97, v16
	s_nop 0
	s_nop 0
	v_addc_co_u32_e32 v21, vcc, 0, v17, vcc
	v_add_co_u32_e32 v24, vcc, s21, v6
	global_load_dword v188, v[20:21], off offset:3072
	s_nop 0
	v_addc_co_u32_e32 v25, vcc, 0, v7, vcc
	global_load_dword v229, v[22:23], off offset:1024
	global_load_dword v228, v[24:25], off offset:3072
	s_nop 0
	s_nop 0
	s_nop 0
	v_mov_b32_dpp v111, v182 row_ror:1 row_mask:0xf bank_mask:0xf
	v_mov_b32_dpp v121, v182 row_ror:2 row_mask:0xf bank_mask:0xf
	v_cndmask_b32_e64 v183, v111, 0, s[38:39]
	v_cndmask_b32_e64 v155, 0, v121, s[40:41]
	v_mov_b32_dpp v123, v184 row_ror:1 row_mask:0xf bank_mask:0xf
	v_mov_b32_dpp v125, v184 row_ror:2 row_mask:0xf bank_mask:0xf
	v_cndmask_b32_e64 v185, v123, 0, s[38:39]
	v_cndmask_b32_e64 v159, 0, v125, s[40:41]
	s_waitcnt vmcnt(5)
	v_pk_mul_f32 v[182:183], v[136:137], v[182:183]
	s_waitcnt vmcnt(4)
	v_fma_f32 v155, v139, v155, v189
	v_add_f32_e32 v155, v183, v155
	v_add_f32_e32 v155, v182, v155
	v_mul_f32_e32 v161, 0xbfb8aa3b, v155
	v_exp_f32_e32 v161, v161
	v_mov_b32_e32 v183, v136
	v_add_f32_e32 v136, 1.0, v161
	v_rcp_f32_e32 v161, v136
	s_waitcnt vmcnt(2)
	v_fma_f32 v159, v138, v159, v188
	v_mul_f32_e32 v155, v155, v161
	s_waitcnt vmcnt(1)
	v_mov_b32_e32 v136, v229
	s_waitcnt vmcnt(0)
	v_pk_mul_f32 v[184:185], v[228:229], v[184:185]
	v_mov_b32_e32 v182, v228
	v_add_f32_e32 v159, v185, v159
	v_add_f32_e32 v159, v184, v159
	v_mul_f32_e32 v184, v159, v155
	s_nop 0
	s_nop 0
	v_mov_b32_dpp v129, v187 row_ror:2 row_mask:0xf bank_mask:0xf
	v_mov_b32_dpp v153, v186 row_ror:2 row_mask:0xf bank_mask:0xf
	v_mov_b32_dpp v127, v187 row_ror:1 row_mask:0xf bank_mask:0xf
	v_mov_b32_dpp v131, v186 row_ror:1 row_mask:0xf bank_mask:0xf
	v_cndmask_b32_e64 v231, v121, v129, s[40:41]
	v_cndmask_b32_e64 v230, v125, v153, s[40:41]
	v_cndmask_b32_e64 v229, v127, v111, s[38:39]
	v_cndmask_b32_e64 v228, v131, v123, s[38:39]
	v_pk_fma_f32 v[230:231], v[138:139], v[230:231], v[188:189]
	v_pk_fma_f32 v[228:229], v[136:137], v[228:229], v[230:231]
	v_pk_fma_f32 v[186:187], v[182:183], v[186:187], v[228:229]
	v_mul_f32_e32 v111, 0xbfb8aa3b, v187
	v_exp_f32_e32 v111, v111
	s_nop 0
	v_add_f32_e32 v111, 1.0, v111
	v_rcp_f32_e32 v111, v111
	s_nop 0
	v_mul_f32_e32 v111, v187, v111
	v_mul_f32_e32 v185, v186, v111
	s_nop 1
	v_mov_b32_dpp v123, v115 row_ror:2 row_mask:0xf bank_mask:0xf
	v_mov_b32_dpp v155, v114 row_ror:2 row_mask:0xf bank_mask:0xf
	v_mov_b32_dpp v121, v115 row_ror:1 row_mask:0xf bank_mask:0xf
	v_mov_b32_dpp v125, v114 row_ror:1 row_mask:0xf bank_mask:0xf
	v_cndmask_b32_e64 v229, v129, v123, s[40:41]
	v_cndmask_b32_e64 v228, v153, v155, s[40:41]
	v_cndmask_b32_e64 v187, v121, v127, s[38:39]
	v_cndmask_b32_e64 v186, v125, v131, s[38:39]
	v_pk_fma_f32 v[228:229], v[138:139], v[228:229], v[188:189]
	v_pk_fma_f32 v[186:187], v[136:137], v[186:187], v[228:229]
	v_pk_fma_f32 v[114:115], v[182:183], v[114:115], v[186:187]
	v_mul_f32_e32 v111, 0xbfb8aa3b, v115
	v_exp_f32_e32 v111, v111
	s_nop 0
	v_add_f32_e32 v111, 1.0, v111
	v_rcp_f32_e32 v111, v111
	s_nop 0
	v_mul_f32_e32 v111, v115, v111
	v_mul_f32_e32 v186, v114, v111
	s_nop 1
	v_mov_b32_dpp v129, v99 row_ror:2 row_mask:0xf bank_mask:0xf
	v_mov_b32_dpp v153, v98 row_ror:2 row_mask:0xf bank_mask:0xf
	v_mov_b32_dpp v127, v99 row_ror:1 row_mask:0xf bank_mask:0xf
	v_mov_b32_dpp v131, v98 row_ror:1 row_mask:0xf bank_mask:0xf
	v_cndmask_b32_e64 v229, v123, v129, s[40:41]
	v_cndmask_b32_e64 v228, v155, v153, s[40:41]
	v_cndmask_b32_e64 v115, v127, v121, s[38:39]
	v_cndmask_b32_e64 v114, v131, v125, s[38:39]
	v_pk_fma_f32 v[228:229], v[138:139], v[228:229], v[188:189]
	v_pk_fma_f32 v[114:115], v[136:137], v[114:115], v[228:229]
	v_pk_fma_f32 v[98:99], v[182:183], v[98:99], v[114:115]
	v_mul_f32_e32 v111, 0xbfb8aa3b, v99
	v_exp_f32_e32 v111, v111
	s_nop 0
	v_add_f32_e32 v111, 1.0, v111
	v_rcp_f32_e32 v111, v111
	s_nop 0
	v_mul_f32_e32 v99, v99, v111
	v_mul_f32_e32 v187, v98, v99
	s_nop 1
	v_mov_b32_dpp v123, v191 row_ror:2 row_mask:0xf bank_mask:0xf
	v_mov_b32_dpp v155, v190 row_ror:2 row_mask:0xf bank_mask:0xf
	v_mov_b32_dpp v121, v191 row_ror:1 row_mask:0xf bank_mask:0xf
	v_mov_b32_dpp v125, v190 row_ror:1 row_mask:0xf bank_mask:0xf
; __device__ __forceinline__ float sigmoidf_(float x) { return __builtin_amdgcn_rcpf(1.0f + __expf(-x)); }
; template <int N> __device__ __forceinline__ float dpp_ror(float v) { return __builtin_bit_cast(float, __builtin_amdgcn_update_dpp(0, __builtin_bit_cast(int, v), 0x120 + N, 0xf, 0xf, false)); }
;     __device__ __forceinline__ void operator()(Acc& acc, const Unit& u, int wr, int wc, int fr, int fq) const {
;     ...
;             for (int i = 0; i < 4; ++i) {
;                 const int cg_ = ch0 + 4 * n + i, cv_ = DFF + cg_;
;                 const float g0 = cw[cg_], g1 = cw[NUP + cg_], g2 = cw[2 * NUP + cg_], gb = cb[cg_];
;                 const float v0 = cw[cv_], v1 = cw[NUP + cv_], v2 = cw[2 * NUP + cv_], vb = cb[cv_];
;                 float pg1 = 0.f, pg2 = 0.f, pv1 = 0.f, pv2 = 0.f;
; #pragma unroll
;                 for (int q = 0; q < 8; ++q) {
;                     float cgv = acc[q >> 2][0][q & 3][n][i], cvv = acc[q >> 2][1][q & 3][n][i];
;                     asm volatile("" : "+v"(cgv), "+v"(cvv) : "v"(chain));
;                     const float tg1 = dpp_ror<1>(cgv), tg2 = dpp_ror<2>(cgv), tv1 = dpp_ror<1>(cvv), tv2 = dpp_ror<2>(cvv);
;                     const float sg1 = fr >= 1 ? tg1 : pg1, sg2 = fr >= 2 ? tg2 : pg2, sv1 = fr >= 1 ? tv1 : pv1, sv2 = fr >= 2 ? tv2 : pv2;
;                     const float gg = gb + g0 * sg2 + g1 * sg1 + g2 * cgv;
;                     const float vv = vb + v0 * sv2 + v1 * sv1 + v2 * cvv;
;                     chain = gg * sigmoidf_(gg) * vv; acc[q >> 2][0][q & 3][n][i] = chain;
;                     pg1 = tg1; pg2 = tg2; pv1 = tv1; pv2 = tv2;
;                 }
	v_cndmask_b32_e64 v115, v129, v123, s[40:41]
	v_cndmask_b32_e64 v114, v153, v155, s[40:41]
	v_cndmask_b32_e64 v99, v121, v127, s[38:39]
	v_cndmask_b32_e64 v98, v125, v131, s[38:39]
	v_pk_fma_f32 v[114:115], v[138:139], v[114:115], v[188:189]
	v_pk_fma_f32 v[98:99], v[136:137], v[98:99], v[114:115]
	v_pk_fma_f32 v[98:99], v[182:183], v[190:191], v[98:99]
	v_mul_f32_e32 v111, 0xbfb8aa3b, v99
	v_exp_f32_e32 v111, v111
	s_nop 0
	v_add_f32_e32 v111, 1.0, v111
	v_rcp_f32_e32 v111, v111
	s_nop 0
	v_mul_f32_e32 v99, v99, v111
	v_mul_f32_e32 v190, v98, v99
	s_nop 1
	v_mov_b32_dpp v129, v193 row_ror:2 row_mask:0xf bank_mask:0xf
	v_mov_b32_dpp v153, v192 row_ror:2 row_mask:0xf bank_mask:0xf
	v_mov_b32_dpp v127, v193 row_ror:1 row_mask:0xf bank_mask:0xf
	v_mov_b32_dpp v131, v192 row_ror:1 row_mask:0xf bank_mask:0xf
	v_cndmask_b32_e64 v115, v123, v129, s[40:41]
	v_cndmask_b32_e64 v114, v155, v153, s[40:41]
	v_cndmask_b32_e64 v99, v127, v121, s[38:39]
	v_cndmask_b32_e64 v98, v131, v125, s[38:39]
	v_pk_fma_f32 v[114:115], v[138:139], v[114:115], v[188:189]
	v_pk_fma_f32 v[98:99], v[136:137], v[98:99], v[114:115]
	v_pk_fma_f32 v[98:99], v[182:183], v[192:193], v[98:99]
	v_mul_f32_e32 v111, 0xbfb8aa3b, v99
	v_exp_f32_e32 v111, v111
	s_nop 0
	v_add_f32_e32 v111, 1.0, v111
	v_rcp_f32_e32 v111, v111
	s_nop 0
	v_mul_f32_e32 v99, v99, v111
	v_mul_f32_e32 v191, v98, v99
	s_nop 1
	v_mov_b32_dpp v123, v133 row_ror:2 row_mask:0xf bank_mask:0xf
	v_mov_b32_dpp v155, v132 row_ror:2 row_mask:0xf bank_mask:0xf
	v_mov_b32_dpp v121, v133 row_ror:1 row_mask:0xf bank_mask:0xf
	v_mov_b32_dpp v125, v132 row_ror:1 row_mask:0xf bank_mask:0xf
	v_cndmask_b32_e64 v115, v129, v123, s[40:41]
	v_cndmask_b32_e64 v114, v153, v155, s[40:41]
	v_cndmask_b32_e64 v99, v121, v127, s[38:39]
	v_cndmask_b32_e64 v98, v125, v131, s[38:39]
	v_pk_fma_f32 v[114:115], v[138:139], v[114:115], v[188:189]
	v_pk_fma_f32 v[98:99], v[136:137], v[98:99], v[114:115]
	v_pk_fma_f32 v[98:99], v[182:183], v[132:133], v[98:99]
	v_mul_f32_e32 v111, 0xbfb8aa3b, v99
	v_exp_f32_e32 v111, v111
	s_nop 0
	v_add_f32_e32 v111, 1.0, v111
	v_rcp_f32_e32 v111, v111
	s_nop 0
	v_mul_f32_e32 v99, v99, v111
	v_mul_f32_e32 v192, v98, v99
	s_nop 1
	v_mov_b32_dpp v114, v135 row_ror:1 row_mask:0xf bank_mask:0xf
	v_mov_b32_dpp v115, v135 row_ror:2 row_mask:0xf bank_mask:0xf
	v_mov_b32_dpp v129, v134 row_ror:2 row_mask:0xf bank_mask:0xf
	v_mov_b32_dpp v127, v134 row_ror:1 row_mask:0xf bank_mask:0xf
	v_cndmask_b32_e64 v99, v114, v121, s[38:39]
	v_cndmask_b32_e64 v115, v123, v115, s[40:41]
	v_cndmask_b32_e64 v114, v155, v129, s[40:41]
	v_cndmask_b32_e64 v98, v127, v125, s[38:39]
	v_pk_fma_f32 v[114:115], v[138:139], v[114:115], v[188:189]
	s_nop 0
	v_pk_fma_f32 v[98:99], v[136:137], v[98:99], v[114:115]
	s_nop 0
	v_pk_fma_f32 v[98:99], v[182:183], v[134:135], v[98:99]
	s_nop 0
	v_mul_f32_e32 v111, 0xbfb8aa3b, v99
	v_exp_f32_e32 v111, v111
	s_nop 0
	v_add_f32_e32 v111, 1.0, v111
	v_rcp_f32_e32 v111, v111
	s_nop 0
	v_mul_f32_e32 v99, v99, v111
	v_mul_f32_e32 v136, v98, v99
	global_load_dword v115, v[6:7], off offset:4
	global_load_dword v99, v[8:9], off offset:2052
	global_load_dword v98, v[10:11], off offset:4
	global_load_dword v133, v[16:17], off offset:4
	global_load_dword v132, v[20:21], off offset:3076
	global_load_dword v114, v[18:19], off offset:3076
	global_load_dword v139, v[22:23], off offset:1028
	global_load_dword v138, v[24:25], off offset:3076
	s_nop 0
	s_nop 0
	v_mov_b32_dpp v111, v176 row_ror:1 row_mask:0xf bank_mask:0xf
	v_mov_b32_dpp v121, v176 row_ror:2 row_mask:0xf bank_mask:0xf
	v_cndmask_b32_e64 v177, v111, 0, s[38:39]
	v_cndmask_b32_e64 v134, 0, v121, s[40:41]
	v_mov_b32_dpp v123, v178 row_ror:1 row_mask:0xf bank_mask:0xf
	v_cndmask_b32_e64 v179, v123, 0, s[38:39]
	v_mov_b32_dpp v125, v178 row_ror:2 row_mask:0xf bank_mask:0xf
	v_cndmask_b32_e64 v137, 0, v125, s[40:41]
	s_waitcnt vmcnt(4)
	v_fma_f32 v155, v115, v134, v133
	v_pk_mul_f32 v[134:135], v[98:99], v[176:177]
	s_waitcnt vmcnt(2)
	v_fma_f32 v137, v114, v137, v132
	v_add_f32_e32 v135, v135, v155
	v_add_f32_e32 v155, v134, v135
	v_mul_f32_e32 v134, 0xbfb8aa3b, v155
	v_exp_f32_e32 v159, v134
	v_mov_b32_e32 v135, v98
	s_waitcnt vmcnt(0)
	v_pk_mul_f32 v[176:177], v[138:139], v[178:179]
	v_mov_b32_e32 v134, v138
	v_add_f32_e32 v98, 1.0, v159
	v_rcp_f32_e32 v138, v98
	v_add_f32_e32 v137, v177, v137
	v_add_f32_e32 v137, v176, v137
	v_mov_b32_e32 v98, v139
	v_mul_f32_e32 v138, v155, v138
	v_mul_f32_e32 v137, v137, v138
	s_nop 0
	s_nop 0
	v_mov_b32_dpp v129, v181 row_ror:2 row_mask:0xf bank_mask:0xf
	v_mov_b32_dpp v153, v180 row_ror:2 row_mask:0xf bank_mask:0xf
	v_mov_b32_dpp v127, v181 row_ror:1 row_mask:0xf bank_mask:0xf
	v_mov_b32_dpp v131, v180 row_ror:1 row_mask:0xf bank_mask:0xf
	v_cndmask_b32_e64 v177, v121, v129, s[40:41]
	v_cndmask_b32_e64 v176, v125, v153, s[40:41]
	v_cndmask_b32_e64 v139, v127, v111, s[38:39]
	v_cndmask_b32_e64 v138, v131, v123, s[38:39]
	v_pk_fma_f32 v[176:177], v[114:115], v[176:177], v[132:133]
	v_pk_fma_f32 v[138:139], v[98:99], v[138:139], v[176:177]
	v_pk_fma_f32 v[138:139], v[134:135], v[180:181], v[138:139]
	v_mul_f32_e32 v111, 0xbfb8aa3b, v139
	v_exp_f32_e32 v111, v111
	s_nop 0
	v_add_f32_e32 v111, 1.0, v111
	v_rcp_f32_e32 v111, v111
	s_nop 0
	v_mul_f32_e32 v111, v139, v111
	v_mul_f32_e32 v138, v138, v111
	s_nop 0
	s_nop 0
	v_mov_b32_dpp v123, v107 row_ror:2 row_mask:0xf bank_mask:0xf
	v_mov_b32_dpp v155, v106 row_ror:2 row_mask:0xf bank_mask:0xf
	v_mov_b32_dpp v121, v107 row_ror:1 row_mask:0xf bank_mask:0xf
	v_mov_b32_dpp v125, v106 row_ror:1 row_mask:0xf bank_mask:0xf
	v_cndmask_b32_e64 v179, v129, v123, s[40:41]
; __device__ __forceinline__ float sigmoidf_(float x) { return __builtin_amdgcn_rcpf(1.0f + __expf(-x)); }
; template <int N> __device__ __forceinline__ float dpp_ror(float v) { return __builtin_bit_cast(float, __builtin_amdgcn_update_dpp(0, __builtin_bit_cast(int, v), 0x120 + N, 0xf, 0xf, false)); }
;     __device__ __forceinline__ void operator()(Acc& acc, const Unit& u, int wr, int wc, int fr, int fq) const {
;     ...
;             for (int i = 0; i < 4; ++i) {
;                 const int cg_ = ch0 + 4 * n + i, cv_ = DFF + cg_;
;                 const float g0 = cw[cg_], g1 = cw[NUP + cg_], g2 = cw[2 * NUP + cg_], gb = cb[cg_];
;                 const float v0 = cw[cv_], v1 = cw[NUP + cv_], v2 = cw[2 * NUP + cv_], vb = cb[cv_];
;                 float pg1 = 0.f, pg2 = 0.f, pv1 = 0.f, pv2 = 0.f;
; #pragma unroll
;                 for (int q = 0; q < 8; ++q) {
;                     float cgv = acc[q >> 2][0][q & 3][n][i], cvv = acc[q >> 2][1][q & 3][n][i];
;                     asm volatile("" : "+v"(cgv), "+v"(cvv) : "v"(chain));
;                     const float tg1 = dpp_ror<1>(cgv), tg2 = dpp_ror<2>(cgv), tv1 = dpp_ror<1>(cvv), tv2 = dpp_ror<2>(cvv);
;                     const float sg1 = fr >= 1 ? tg1 : pg1, sg2 = fr >= 2 ? tg2 : pg2, sv1 = fr >= 1 ? tv1 : pv1, sv2 = fr >= 2 ? tv2 : pv2;
;                     const float gg = gb + g0 * sg2 + g1 * sg1 + g2 * cgv;
;                     const float vv = vb + v0 * sv2 + v1 * sv1 + v2 * cvv;
;                     chain = gg * sigmoidf_(gg) * vv; acc[q >> 2][0][q & 3][n][i] = chain;
;                     pg1 = tg1; pg2 = tg2; pv1 = tv1; pv2 = tv2;
;                 }
	v_cndmask_b32_e64 v178, v153, v155, s[40:41]
	v_cndmask_b32_e64 v177, v121, v127, s[38:39]
	v_cndmask_b32_e64 v176, v125, v131, s[38:39]
	v_pk_fma_f32 v[178:179], v[114:115], v[178:179], v[132:133]
	v_pk_fma_f32 v[176:177], v[98:99], v[176:177], v[178:179]
	v_pk_fma_f32 v[106:107], v[134:135], v[106:107], v[176:177]
	v_mul_f32_e32 v111, 0xbfb8aa3b, v107
	v_exp_f32_e32 v111, v111
	s_nop 0
	v_add_f32_e32 v111, 1.0, v111
	v_rcp_f32_e32 v111, v111
	s_nop 0
	v_mul_f32_e32 v107, v107, v111
	v_mul_f32_e32 v106, v106, v107
	s_nop 0
	s_nop 0
	v_mov_b32_dpp v129, v91 row_ror:2 row_mask:0xf bank_mask:0xf
	v_mov_b32_dpp v139, v90 row_ror:2 row_mask:0xf bank_mask:0xf
	v_mov_b32_dpp v127, v91 row_ror:1 row_mask:0xf bank_mask:0xf
	v_mov_b32_dpp v131, v90 row_ror:1 row_mask:0xf bank_mask:0xf
	v_cndmask_b32_e64 v179, v123, v129, s[40:41]
	v_cndmask_b32_e64 v178, v155, v139, s[40:41]
	v_cndmask_b32_e64 v177, v127, v121, s[38:39]
	v_cndmask_b32_e64 v176, v131, v125, s[38:39]
	v_pk_fma_f32 v[178:179], v[114:115], v[178:179], v[132:133]
	v_pk_fma_f32 v[176:177], v[98:99], v[176:177], v[178:179]
	v_pk_fma_f32 v[90:91], v[134:135], v[90:91], v[176:177]
	v_mul_f32_e32 v107, 0xbfb8aa3b, v91
	v_exp_f32_e32 v107, v107
	s_nop 0
	v_add_f32_e32 v107, 1.0, v107
	v_rcp_f32_e32 v107, v107
	s_nop 0
	v_mul_f32_e32 v91, v91, v107
	v_mul_f32_e32 v90, v90, v91
	s_nop 1
	v_mov_b32_dpp v121, v75 row_ror:2 row_mask:0xf bank_mask:0xf
	v_mov_b32_dpp v125, v74 row_ror:2 row_mask:0xf bank_mask:0xf
	v_mov_b32_dpp v111, v75 row_ror:1 row_mask:0xf bank_mask:0xf
	v_mov_b32_dpp v123, v74 row_ror:1 row_mask:0xf bank_mask:0xf
	v_cndmask_b32_e64 v179, v129, v121, s[40:41]
	v_cndmask_b32_e64 v178, v139, v125, s[40:41]
	v_cndmask_b32_e64 v177, v111, v127, s[38:39]
	v_cndmask_b32_e64 v176, v123, v131, s[38:39]
	v_pk_fma_f32 v[178:179], v[114:115], v[178:179], v[132:133]
	v_pk_fma_f32 v[176:177], v[98:99], v[176:177], v[178:179]
	v_pk_fma_f32 v[74:75], v[134:135], v[74:75], v[176:177]
	v_mul_f32_e32 v91, 0xbfb8aa3b, v75
	v_exp_f32_e32 v91, v91
	s_nop 0
	v_add_f32_e32 v91, 1.0, v91
	v_rcp_f32_e32 v91, v91
	s_nop 0
	v_mul_f32_e32 v75, v75, v91
	v_mul_f32_e32 v91, v74, v75
	s_nop 1
	v_mov_b32_dpp v129, v59 row_ror:2 row_mask:0xf bank_mask:0xf
	v_mov_b32_dpp v139, v58 row_ror:2 row_mask:0xf bank_mask:0xf
	v_mov_b32_dpp v127, v59 row_ror:1 row_mask:0xf bank_mask:0xf
	v_mov_b32_dpp v131, v58 row_ror:1 row_mask:0xf bank_mask:0xf
	v_cndmask_b32_e64 v177, v121, v129, s[40:41]
	v_cndmask_b32_e64 v176, v125, v139, s[40:41]
	v_cndmask_b32_e64 v75, v127, v111, s[38:39]
	v_cndmask_b32_e64 v74, v131, v123, s[38:39]
	v_pk_fma_f32 v[176:177], v[114:115], v[176:177], v[132:133]
	v_pk_fma_f32 v[74:75], v[98:99], v[74:75], v[176:177]
	v_pk_fma_f32 v[58:59], v[134:135], v[58:59], v[74:75]
	v_mul_f32_e32 v74, 0xbfb8aa3b, v59
	v_exp_f32_e32 v74, v74
	s_nop 0
	v_add_f32_e32 v74, 1.0, v74
	v_rcp_f32_e32 v74, v74
	s_nop 0
	v_mul_f32_e32 v59, v59, v74
	v_mul_f32_e32 v107, v58, v59
	s_nop 1
	v_mov_b32_dpp v121, v63 row_ror:2 row_mask:0xf bank_mask:0xf
	v_mov_b32_dpp v125, v62 row_ror:2 row_mask:0xf bank_mask:0xf
	v_mov_b32_dpp v111, v63 row_ror:1 row_mask:0xf bank_mask:0xf
	v_mov_b32_dpp v123, v62 row_ror:1 row_mask:0xf bank_mask:0xf
	v_cndmask_b32_e64 v75, v129, v121, s[40:41]
	v_cndmask_b32_e64 v74, v139, v125, s[40:41]
	v_cndmask_b32_e64 v59, v111, v127, s[38:39]
	v_cndmask_b32_e64 v58, v123, v131, s[38:39]
	v_pk_fma_f32 v[74:75], v[114:115], v[74:75], v[132:133]
	v_pk_fma_f32 v[58:59], v[98:99], v[58:59], v[74:75]
	v_pk_fma_f32 v[58:59], v[134:135], v[62:63], v[58:59]
	v_mul_f32_e32 v62, 0xbfb8aa3b, v59
	v_exp_f32_e32 v62, v62
	s_nop 0
	v_add_f32_e32 v62, 1.0, v62
	v_rcp_f32_e32 v62, v62
	s_nop 0
	v_mul_f32_e32 v59, v59, v62
	v_mul_f32_e32 v139, v58, v59
	s_nop 1
	v_mov_b32_dpp v63, v83 row_ror:1 row_mask:0xf bank_mask:0xf
	v_mov_b32_dpp v74, v83 row_ror:2 row_mask:0xf bank_mask:0xf
	v_mov_b32_dpp v127, v82 row_ror:2 row_mask:0xf bank_mask:0xf
	v_mov_b32_dpp v75, v82 row_ror:1 row_mask:0xf bank_mask:0xf
	v_cndmask_b32_e64 v59, v63, v111, s[38:39]
	v_cndmask_b32_e64 v63, v121, v74, s[40:41]
	v_cndmask_b32_e64 v62, v125, v127, s[40:41]
	v_cndmask_b32_e64 v58, v75, v123, s[38:39]
	v_pk_fma_f32 v[62:63], v[114:115], v[62:63], v[132:133]
	s_nop 0
	v_pk_fma_f32 v[58:59], v[98:99], v[58:59], v[62:63]
	s_nop 0
	v_pk_fma_f32 v[58:59], v[134:135], v[82:83], v[58:59]
	s_nop 0
	v_mul_f32_e32 v62, 0xbfb8aa3b, v59
	v_exp_f32_e32 v62, v62
	s_nop 0
	v_add_f32_e32 v62, 1.0, v62
	v_rcp_f32_e32 v62, v62
	s_nop 0
	v_mul_f32_e32 v59, v59, v62
	v_mul_f32_e32 v98, v58, v59
	global_load_dword v63, v[6:7], off offset:8
	global_load_dword v59, v[8:9], off offset:2056
	global_load_dword v58, v[10:11], off offset:8
	global_load_dword v75, v[16:17], off offset:8
	global_load_dword v74, v[20:21], off offset:3080
	global_load_dword v62, v[18:19], off offset:3080
	global_load_dword v115, v[22:23], off offset:1032
	global_load_dword v114, v[24:25], off offset:3080
	s_nop 0
	s_nop 0
	v_mov_b32_dpp v111, v160 row_ror:1 row_mask:0xf bank_mask:0xf
	v_mov_b32_dpp v121, v160 row_ror:2 row_mask:0xf bank_mask:0xf
	v_cndmask_b32_e64 v161, v111, 0, s[38:39]
	v_cndmask_b32_e64 v82, 0, v121, s[40:41]
	v_mov_b32_dpp v123, v162 row_ror:1 row_mask:0xf bank_mask:0xf
	v_cndmask_b32_e64 v163, v123, 0, s[38:39]
	v_mov_b32_dpp v125, v162 row_ror:2 row_mask:0xf bank_mask:0xf
	v_cndmask_b32_e64 v99, 0, v125, s[40:41]
	s_waitcnt vmcnt(4)
	v_fma_f32 v132, v63, v82, v75
	v_pk_mul_f32 v[82:83], v[58:59], v[160:161]
	s_waitcnt vmcnt(2)
	v_fma_f32 v99, v62, v99, v74
	v_add_f32_e32 v83, v83, v132
	v_add_f32_e32 v135, v82, v83
	v_mul_f32_e32 v82, 0xbfb8aa3b, v135
	v_exp_f32_e32 v153, v82
	v_mov_b32_e32 v83, v58
	s_waitcnt vmcnt(0)
; __device__ __forceinline__ float sigmoidf_(float x) { return __builtin_amdgcn_rcpf(1.0f + __expf(-x)); }
; template <int N> __device__ __forceinline__ float dpp_ror(float v) { return __builtin_bit_cast(float, __builtin_amdgcn_update_dpp(0, __builtin_bit_cast(int, v), 0x120 + N, 0xf, 0xf, false)); }
;     __device__ __forceinline__ void operator()(Acc& acc, const Unit& u, int wr, int wc, int fr, int fq) const {
;     ...
;             for (int i = 0; i < 4; ++i) {
;                 const int cg_ = ch0 + 4 * n + i, cv_ = DFF + cg_;
;                 const float g0 = cw[cg_], g1 = cw[NUP + cg_], g2 = cw[2 * NUP + cg_], gb = cb[cg_];
;                 const float v0 = cw[cv_], v1 = cw[NUP + cv_], v2 = cw[2 * NUP + cv_], vb = cb[cv_];
;                 float pg1 = 0.f, pg2 = 0.f, pv1 = 0.f, pv2 = 0.f;
; #pragma unroll
;                 for (int q = 0; q < 8; ++q) {
;                     float cgv = acc[q >> 2][0][q & 3][n][i], cvv = acc[q >> 2][1][q & 3][n][i];
;                     asm volatile("" : "+v"(cgv), "+v"(cvv) : "v"(chain));
;                     const float tg1 = dpp_ror<1>(cgv), tg2 = dpp_ror<2>(cgv), tv1 = dpp_ror<1>(cvv), tv2 = dpp_ror<2>(cvv);
;                     const float sg1 = fr >= 1 ? tg1 : pg1, sg2 = fr >= 2 ? tg2 : pg2, sv1 = fr >= 1 ? tv1 : pv1, sv2 = fr >= 2 ? tv2 : pv2;
;                     const float gg = gb + g0 * sg2 + g1 * sg1 + g2 * cgv;
;                     const float vv = vb + v0 * sv2 + v1 * sv1 + v2 * cvv;
;                     chain = gg * sigmoidf_(gg) * vv; acc[q >> 2][0][q & 3][n][i] = chain;
;                     pg1 = tg1; pg2 = tg2; pv1 = tv1; pv2 = tv2;
;                 }
	v_pk_mul_f32 v[132:133], v[114:115], v[162:163]
	v_mov_b32_e32 v82, v114
	v_add_f32_e32 v58, 1.0, v153
	v_rcp_f32_e32 v114, v58
	v_add_f32_e32 v99, v133, v99
	v_add_f32_e32 v99, v132, v99
	v_mov_b32_e32 v58, v115
	v_mul_f32_e32 v114, v135, v114
	v_mul_f32_e32 v99, v99, v114
	s_nop 0
	s_nop 0
	v_mov_b32_dpp v129, v175 row_ror:2 row_mask:0xf bank_mask:0xf
	v_mov_b32_dpp v134, v174 row_ror:2 row_mask:0xf bank_mask:0xf
	v_mov_b32_dpp v127, v175 row_ror:1 row_mask:0xf bank_mask:0xf
	v_mov_b32_dpp v131, v174 row_ror:1 row_mask:0xf bank_mask:0xf
	v_cndmask_b32_e64 v133, v121, v129, s[40:41]
	v_cndmask_b32_e64 v132, v125, v134, s[40:41]
	v_cndmask_b32_e64 v115, v127, v111, s[38:39]
	v_cndmask_b32_e64 v114, v131, v123, s[38:39]
	v_pk_fma_f32 v[132:133], v[62:63], v[132:133], v[74:75]
	v_pk_fma_f32 v[114:115], v[58:59], v[114:115], v[132:133]
	v_pk_fma_f32 v[114:115], v[82:83], v[174:175], v[114:115]
	v_mul_f32_e32 v111, 0xbfb8aa3b, v115
	v_exp_f32_e32 v111, v111
	s_nop 0
	v_add_f32_e32 v111, 1.0, v111
	v_rcp_f32_e32 v111, v111
	s_nop 0
	v_mul_f32_e32 v111, v115, v111
	v_mul_f32_e32 v114, v114, v111
	s_nop 0
	s_nop 0
	v_mov_b32_dpp v123, v105 row_ror:2 row_mask:0xf bank_mask:0xf
	v_mov_b32_dpp v153, v104 row_ror:2 row_mask:0xf bank_mask:0xf
	v_mov_b32_dpp v121, v105 row_ror:1 row_mask:0xf bank_mask:0xf
	v_mov_b32_dpp v125, v104 row_ror:1 row_mask:0xf bank_mask:0xf
	v_cndmask_b32_e64 v135, v129, v123, s[40:41]
	v_cndmask_b32_e64 v134, v134, v153, s[40:41]
	v_cndmask_b32_e64 v133, v121, v127, s[38:39]
	v_cndmask_b32_e64 v132, v125, v131, s[38:39]
	v_pk_fma_f32 v[134:135], v[62:63], v[134:135], v[74:75]
	v_pk_fma_f32 v[132:133], v[58:59], v[132:133], v[134:135]
	v_pk_fma_f32 v[104:105], v[82:83], v[104:105], v[132:133]
	v_mul_f32_e32 v111, 0xbfb8aa3b, v105
	v_exp_f32_e32 v111, v111
	s_nop 0
	v_add_f32_e32 v111, 1.0, v111
	v_rcp_f32_e32 v111, v111
	s_nop 0
	v_mul_f32_e32 v105, v105, v111
	v_mul_f32_e32 v104, v104, v105
	s_nop 0
	s_nop 0
	v_mov_b32_dpp v127, v89 row_ror:2 row_mask:0xf bank_mask:0xf
	v_mov_b32_dpp v131, v88 row_ror:2 row_mask:0xf bank_mask:0xf
	v_mov_b32_dpp v115, v89 row_ror:1 row_mask:0xf bank_mask:0xf
	v_mov_b32_dpp v129, v88 row_ror:1 row_mask:0xf bank_mask:0xf
	v_cndmask_b32_e64 v135, v123, v127, s[40:41]
	v_cndmask_b32_e64 v134, v153, v131, s[40:41]
	v_cndmask_b32_e64 v133, v115, v121, s[38:39]
	v_cndmask_b32_e64 v132, v129, v125, s[38:39]
	v_pk_fma_f32 v[134:135], v[62:63], v[134:135], v[74:75]
	v_pk_fma_f32 v[132:133], v[58:59], v[132:133], v[134:135]
	v_pk_fma_f32 v[88:89], v[82:83], v[88:89], v[132:133]
	v_mul_f32_e32 v105, 0xbfb8aa3b, v89
	v_exp_f32_e32 v105, v105
	s_nop 0
	v_add_f32_e32 v105, 1.0, v105
	v_rcp_f32_e32 v105, v105
	s_nop 0
	v_mul_f32_e32 v89, v89, v105
	v_mul_f32_e32 v88, v88, v89
	s_nop 0
	s_nop 0
	v_mov_b32_dpp v121, v73 row_ror:2 row_mask:0xf bank_mask:0xf
	v_mov_b32_dpp v125, v72 row_ror:2 row_mask:0xf bank_mask:0xf
	v_mov_b32_dpp v111, v73 row_ror:1 row_mask:0xf bank_mask:0xf
	v_mov_b32_dpp v123, v72 row_ror:1 row_mask:0xf bank_mask:0xf
	v_cndmask_b32_e64 v135, v127, v121, s[40:41]
	v_cndmask_b32_e64 v134, v131, v125, s[40:41]
	v_cndmask_b32_e64 v133, v111, v115, s[38:39]
	v_cndmask_b32_e64 v132, v123, v129, s[38:39]
	v_pk_fma_f32 v[134:135], v[62:63], v[134:135], v[74:75]
	v_pk_fma_f32 v[132:133], v[58:59], v[132:133], v[134:135]
	v_pk_fma_f32 v[72:73], v[82:83], v[72:73], v[132:133]
	v_mul_f32_e32 v89, 0xbfb8aa3b, v73
	v_exp_f32_e32 v89, v89
	s_nop 0
	v_add_f32_e32 v89, 1.0, v89
	v_rcp_f32_e32 v89, v89
	s_nop 0
	v_mul_f32_e32 v73, v73, v89
	v_mul_f32_e32 v72, v72, v73
	s_nop 1
	v_mov_b32_dpp v115, v57 row_ror:2 row_mask:0xf bank_mask:0xf
	v_mov_b32_dpp v129, v56 row_ror:2 row_mask:0xf bank_mask:0xf
	v_mov_b32_dpp v105, v57 row_ror:1 row_mask:0xf bank_mask:0xf
	v_mov_b32_dpp v127, v56 row_ror:1 row_mask:0xf bank_mask:0xf
	v_cndmask_b32_e64 v135, v121, v115, s[40:41]
	v_cndmask_b32_e64 v134, v125, v129, s[40:41]
	v_cndmask_b32_e64 v133, v105, v111, s[38:39]
	v_cndmask_b32_e64 v132, v127, v123, s[38:39]
	v_pk_fma_f32 v[134:135], v[62:63], v[134:135], v[74:75]
	v_pk_fma_f32 v[132:133], v[58:59], v[132:133], v[134:135]
	v_pk_fma_f32 v[56:57], v[82:83], v[56:57], v[132:133]
	v_mul_f32_e32 v73, 0xbfb8aa3b, v57
	v_exp_f32_e32 v73, v73
	s_nop 0
	v_add_f32_e32 v73, 1.0, v73
	v_rcp_f32_e32 v73, v73
	s_nop 0
	v_mul_f32_e32 v57, v57, v73
	v_mul_f32_e32 v73, v56, v57
	s_nop 1
	v_mov_b32_dpp v121, v43 row_ror:2 row_mask:0xf bank_mask:0xf
	v_mov_b32_dpp v125, v42 row_ror:2 row_mask:0xf bank_mask:0xf
	v_mov_b32_dpp v111, v43 row_ror:1 row_mask:0xf bank_mask:0xf
	v_mov_b32_dpp v123, v42 row_ror:1 row_mask:0xf bank_mask:0xf
	v_cndmask_b32_e64 v133, v115, v121, s[40:41]
	v_cndmask_b32_e64 v132, v129, v125, s[40:41]
	v_cndmask_b32_e64 v57, v111, v105, s[38:39]
	v_cndmask_b32_e64 v56, v123, v127, s[38:39]
	v_pk_fma_f32 v[132:133], v[62:63], v[132:133], v[74:75]
	v_pk_fma_f32 v[56:57], v[58:59], v[56:57], v[132:133]
	v_pk_fma_f32 v[42:43], v[82:83], v[42:43], v[56:57]
	v_mul_f32_e32 v56, 0xbfb8aa3b, v43
	v_exp_f32_e32 v56, v56
	s_nop 0
	v_add_f32_e32 v56, 1.0, v56
	v_rcp_f32_e32 v56, v56
	s_nop 0
	v_mul_f32_e32 v43, v43, v56
	v_mul_f32_e32 v89, v42, v43
	s_nop 1
	v_mov_b32_dpp v57, v51 row_ror:1 row_mask:0xf bank_mask:0xf
	v_mov_b32_dpp v105, v51 row_ror:2 row_mask:0xf bank_mask:0xf
	v_mov_b32_dpp v127, v50 row_ror:2 row_mask:0xf bank_mask:0xf
	v_mov_b32_dpp v115, v50 row_ror:1 row_mask:0xf bank_mask:0xf
	v_cndmask_b32_e64 v43, v57, v111, s[38:39]
	v_cndmask_b32_e64 v57, v121, v105, s[40:41]
	v_cndmask_b32_e64 v56, v125, v127, s[40:41]
	v_cndmask_b32_e64 v42, v115, v123, s[38:39]
	v_pk_fma_f32 v[56:57], v[62:63], v[56:57], v[74:75]
	s_nop 0
	v_pk_fma_f32 v[42:43], v[58:59], v[42:43], v[56:57]
	s_nop 0
	v_pk_fma_f32 v[42:43], v[82:83], v[50:51], v[42:43]
	s_nop 0
	v_mul_f32_e32 v50, 0xbfb8aa3b, v43
	v_exp_f32_e32 v50, v50
	s_nop 0
	v_add_f32_e32 v50, 1.0, v50
	v_rcp_f32_e32 v50, v50
	s_nop 0
	v_mul_f32_e32 v43, v43, v50
	v_mul_f32_e32 v62, v42, v43
	global_load_dword v51, v[6:7], off offset:12
	global_load_dword v43, v[8:9], off offset:2060
	global_load_dword v42, v[10:11], off offset:12
	global_load_dword v57, v[16:17], off offset:12
	global_load_dword v56, v[20:21], off offset:3084
	global_load_dword v50, v[18:19], off offset:3084
	global_load_dword v75, v[22:23], off offset:1036
	global_load_dword v74, v[24:25], off offset:3084
	s_nop 0
	s_nop 0
	v_mov_b32_dpp v105, v154 row_ror:1 row_mask:0xf bank_mask:0xf
	v_mov_b32_dpp v111, v154 row_ror:2 row_mask:0xf bank_mask:0xf
	v_cndmask_b32_e64 v155, v105, 0, s[38:39]
	v_cndmask_b32_e64 v58, 0, v111, s[40:41]
	v_mov_b32_dpp v115, v158 row_ror:1 row_mask:0xf bank_mask:0xf
	v_cndmask_b32_e64 v159, v115, 0, s[38:39]
	v_mov_b32_dpp v121, v158 row_ror:2 row_mask:0xf bank_mask:0xf
	v_cndmask_b32_e64 v63, 0, v121, s[40:41]
	s_waitcnt vmcnt(4)
; __device__ __forceinline__ float sigmoidf_(float x) { return __builtin_amdgcn_rcpf(1.0f + __expf(-x)); }
; template <int N> __device__ __forceinline__ float dpp_ror(float v) { return __builtin_bit_cast(float, __builtin_amdgcn_update_dpp(0, __builtin_bit_cast(int, v), 0x120 + N, 0xf, 0xf, false)); }
;     __device__ __forceinline__ void operator()(Acc& acc, const Unit& u, int wr, int wc, int fr, int fq) const {
;     ...
;             for (int i = 0; i < 4; ++i) {
;                 const int cg_ = ch0 + 4 * n + i, cv_ = DFF + cg_;
;                 const float g0 = cw[cg_], g1 = cw[NUP + cg_], g2 = cw[2 * NUP + cg_], gb = cb[cg_];
;                 const float v0 = cw[cv_], v1 = cw[NUP + cv_], v2 = cw[2 * NUP + cv_], vb = cb[cv_];
;                 float pg1 = 0.f, pg2 = 0.f, pv1 = 0.f, pv2 = 0.f;
; #pragma unroll
;                 for (int q = 0; q < 8; ++q) {
;                     float cgv = acc[q >> 2][0][q & 3][n][i], cvv = acc[q >> 2][1][q & 3][n][i];
;                     asm volatile("" : "+v"(cgv), "+v"(cvv) : "v"(chain));
;                     const float tg1 = dpp_ror<1>(cgv), tg2 = dpp_ror<2>(cgv), tv1 = dpp_ror<1>(cvv), tv2 = dpp_ror<2>(cvv);
;                     const float sg1 = fr >= 1 ? tg1 : pg1, sg2 = fr >= 2 ? tg2 : pg2, sv1 = fr >= 1 ? tv1 : pv1, sv2 = fr >= 2 ? tv2 : pv2;
;                     const float gg = gb + g0 * sg2 + g1 * sg1 + g2 * cgv;
;                     const float vv = vb + v0 * sv2 + v1 * sv1 + v2 * cvv;
;                     chain = gg * sigmoidf_(gg) * vv; acc[q >> 2][0][q & 3][n][i] = chain;
;                     pg1 = tg1; pg2 = tg2; pv1 = tv1; pv2 = tv2;
;                 }
	v_fma_f32 v82, v51, v58, v57
	v_pk_mul_f32 v[58:59], v[42:43], v[154:155]
	s_waitcnt vmcnt(2)
	v_fma_f32 v63, v50, v63, v56
	v_add_f32_e32 v59, v59, v82
	v_add_f32_e32 v131, v58, v59
	v_mul_f32_e32 v58, 0xbfb8aa3b, v131
	v_exp_f32_e32 v132, v58
	v_mov_b32_e32 v59, v42
	s_waitcnt vmcnt(0)
	v_pk_mul_f32 v[82:83], v[74:75], v[158:159]
	v_mov_b32_e32 v58, v74
	v_add_f32_e32 v42, 1.0, v132
	v_rcp_f32_e32 v74, v42
	v_add_f32_e32 v63, v83, v63
	v_add_f32_e32 v63, v82, v63
	v_mov_b32_e32 v42, v75
	v_mul_f32_e32 v74, v131, v74
	v_mul_f32_e32 v63, v63, v74
	s_nop 1
	v_mov_b32_dpp v125, v157 row_ror:2 row_mask:0xf bank_mask:0xf
	v_mov_b32_dpp v129, v156 row_ror:2 row_mask:0xf bank_mask:0xf
	v_mov_b32_dpp v123, v157 row_ror:1 row_mask:0xf bank_mask:0xf
	v_mov_b32_dpp v127, v156 row_ror:1 row_mask:0xf bank_mask:0xf
	v_cndmask_b32_e64 v83, v111, v125, s[40:41]
	v_cndmask_b32_e64 v82, v121, v129, s[40:41]
	v_cndmask_b32_e64 v75, v123, v105, s[38:39]
	v_cndmask_b32_e64 v74, v127, v115, s[38:39]
	v_pk_fma_f32 v[82:83], v[50:51], v[82:83], v[56:57]
	v_pk_fma_f32 v[74:75], v[42:43], v[74:75], v[82:83]
	v_pk_fma_f32 v[74:75], v[58:59], v[156:157], v[74:75]
	v_mul_f32_e32 v82, 0xbfb8aa3b, v75
	v_exp_f32_e32 v82, v82
	s_nop 0
	v_add_f32_e32 v82, 1.0, v82
	v_rcp_f32_e32 v82, v82
	s_nop 0
	v_mul_f32_e32 v75, v75, v82
	v_mul_f32_e32 v74, v74, v75
	s_nop 1
	v_mov_b32_dpp v111, v103 row_ror:2 row_mask:0xf bank_mask:0xf
	v_mov_b32_dpp v121, v102 row_ror:2 row_mask:0xf bank_mask:0xf
	v_mov_b32_dpp v105, v103 row_ror:1 row_mask:0xf bank_mask:0xf
	v_mov_b32_dpp v115, v102 row_ror:1 row_mask:0xf bank_mask:0xf
	v_cndmask_b32_e64 v133, v125, v111, s[40:41]
	v_cndmask_b32_e64 v132, v129, v121, s[40:41]
	v_cndmask_b32_e64 v83, v105, v123, s[38:39]
	v_cndmask_b32_e64 v82, v115, v127, s[38:39]
	v_pk_fma_f32 v[132:133], v[50:51], v[132:133], v[56:57]
	v_pk_fma_f32 v[82:83], v[42:43], v[82:83], v[132:133]
	v_pk_fma_f32 v[82:83], v[58:59], v[102:103], v[82:83]
	v_mul_f32_e32 v75, 0xbfb8aa3b, v83
	v_exp_f32_e32 v75, v75
	s_nop 0
	v_add_f32_e32 v75, 1.0, v75
	v_rcp_f32_e32 v75, v75
	s_nop 0
	v_mul_f32_e32 v75, v83, v75
	v_mul_f32_e32 v75, v82, v75
	s_nop 1
	v_mov_b32_dpp v125, v87 row_ror:2 row_mask:0xf bank_mask:0xf
	v_mov_b32_dpp v129, v86 row_ror:2 row_mask:0xf bank_mask:0xf
	v_mov_b32_dpp v123, v87 row_ror:1 row_mask:0xf bank_mask:0xf
	v_mov_b32_dpp v127, v86 row_ror:1 row_mask:0xf bank_mask:0xf
	v_cndmask_b32_e64 v103, v111, v125, s[40:41]
	v_cndmask_b32_e64 v102, v121, v129, s[40:41]
	v_cndmask_b32_e64 v83, v123, v105, s[38:39]
	v_cndmask_b32_e64 v82, v127, v115, s[38:39]
	v_pk_fma_f32 v[102:103], v[50:51], v[102:103], v[56:57]
	v_pk_fma_f32 v[82:83], v[42:43], v[82:83], v[102:103]
	v_pk_fma_f32 v[82:83], v[58:59], v[86:87], v[82:83]
	v_mul_f32_e32 v86, 0xbfb8aa3b, v83
	v_exp_f32_e32 v86, v86
	s_nop 0
	v_add_f32_e32 v86, 1.0, v86
	v_rcp_f32_e32 v86, v86
	s_nop 0
	v_mul_f32_e32 v83, v83, v86
	v_mul_f32_e32 v82, v82, v83
	s_nop 1
	v_mov_b32_dpp v111, v71 row_ror:2 row_mask:0xf bank_mask:0xf
	v_mov_b32_dpp v121, v70 row_ror:2 row_mask:0xf bank_mask:0xf
	v_mov_b32_dpp v105, v71 row_ror:1 row_mask:0xf bank_mask:0xf
	v_mov_b32_dpp v115, v70 row_ror:1 row_mask:0xf bank_mask:0xf
	v_cndmask_b32_e64 v103, v125, v111, s[40:41]
	v_cndmask_b32_e64 v102, v129, v121, s[40:41]
	v_cndmask_b32_e64 v87, v105, v123, s[38:39]
	v_cndmask_b32_e64 v86, v115, v127, s[38:39]
	v_pk_fma_f32 v[102:103], v[50:51], v[102:103], v[56:57]
	v_pk_fma_f32 v[86:87], v[42:43], v[86:87], v[102:103]
	v_pk_fma_f32 v[70:71], v[58:59], v[70:71], v[86:87]
	v_mul_f32_e32 v83, 0xbfb8aa3b, v71
	v_exp_f32_e32 v83, v83
	s_nop 0
	v_add_f32_e32 v83, 1.0, v83
	v_rcp_f32_e32 v83, v83
	s_nop 0
	v_mul_f32_e32 v71, v71, v83
	v_mul_f32_e32 v70, v70, v71
	s_nop 0
	s_nop 0
	v_mov_b32_dpp v125, v55 row_ror:2 row_mask:0xf bank_mask:0xf
	v_mov_b32_dpp v129, v54 row_ror:2 row_mask:0xf bank_mask:0xf
	v_mov_b32_dpp v123, v55 row_ror:1 row_mask:0xf bank_mask:0xf
	v_mov_b32_dpp v127, v54 row_ror:1 row_mask:0xf bank_mask:0xf
	v_cndmask_b32_e64 v103, v111, v125, s[40:41]
	v_cndmask_b32_e64 v102, v121, v129, s[40:41]
	v_cndmask_b32_e64 v87, v123, v105, s[38:39]
	v_cndmask_b32_e64 v86, v127, v115, s[38:39]
	v_pk_fma_f32 v[102:103], v[50:51], v[102:103], v[56:57]
	v_pk_fma_f32 v[86:87], v[42:43], v[86:87], v[102:103]
	v_pk_fma_f32 v[54:55], v[58:59], v[54:55], v[86:87]
	v_mul_f32_e32 v71, 0xbfb8aa3b, v55
	v_exp_f32_e32 v71, v71
	s_nop 0
	v_add_f32_e32 v71, 1.0, v71
	v_rcp_f32_e32 v71, v71
	s_nop 0
	v_mul_f32_e32 v55, v55, v71
	v_mul_f32_e32 v55, v54, v55
	s_nop 1
	v_mov_b32_dpp v105, v39 row_ror:2 row_mask:0xf bank_mask:0xf
	v_mov_b32_dpp v115, v38 row_ror:2 row_mask:0xf bank_mask:0xf
	v_mov_b32_dpp v83, v39 row_ror:1 row_mask:0xf bank_mask:0xf
	v_mov_b32_dpp v111, v38 row_ror:1 row_mask:0xf bank_mask:0xf
	v_cndmask_b32_e64 v103, v125, v105, s[40:41]
	v_cndmask_b32_e64 v102, v129, v115, s[40:41]
	v_cndmask_b32_e64 v87, v83, v123, s[38:39]
	v_cndmask_b32_e64 v86, v111, v127, s[38:39]
	v_pk_fma_f32 v[102:103], v[50:51], v[102:103], v[56:57]
	s_nop 0
	v_pk_fma_f32 v[86:87], v[42:43], v[86:87], v[102:103]
	v_pk_fma_f32 v[38:39], v[58:59], v[38:39], v[86:87]
	v_mul_f32_e32 v54, 0xbfb8aa3b, v39
	v_exp_f32_e32 v54, v54
	s_nop 0
	v_add_f32_e32 v54, 1.0, v54
	v_rcp_f32_e32 v54, v54
	s_nop 0
	v_mul_f32_e32 v39, v39, v54
	v_mul_f32_e32 v71, v38, v39
	s_nop 1
	v_mov_b32_dpp v86, v41 row_ror:1 row_mask:0xf bank_mask:0xf
	v_mov_b32_dpp v87, v41 row_ror:2 row_mask:0xf bank_mask:0xf
	v_mov_b32_dpp v103, v40 row_ror:2 row_mask:0xf bank_mask:0xf
	v_mov_b32_dpp v102, v40 row_ror:1 row_mask:0xf bank_mask:0xf
	v_cndmask_b32_e64 v39, v86, v83, s[38:39]
	v_cndmask_b32_e64 v87, v105, v87, s[40:41]
	v_cndmask_b32_e64 v86, v115, v103, s[40:41]
	v_cndmask_b32_e64 v38, v102, v111, s[38:39]
	v_pk_fma_f32 v[50:51], v[50:51], v[86:87], v[56:57]
	s_nop 0
	v_pk_fma_f32 v[38:39], v[42:43], v[38:39], v[50:51]
	s_nop 0
	v_pk_fma_f32 v[38:39], v[58:59], v[40:41], v[38:39]
	s_nop 0
	v_mul_f32_e32 v40, 0xbfb8aa3b, v39
	v_exp_f32_e32 v40, v40
	s_nop 0
	v_add_f32_e32 v40, 1.0, v40
	v_rcp_f32_e32 v40, v40
	s_nop 0
	v_mul_f32_e32 v39, v39, v40
	v_mul_f32_e32 v54, v38, v39
	global_load_dword v41, v[6:7], off offset:16
	global_load_dword v39, v[8:9], off offset:2064
	global_load_dword v38, v[10:11], off offset:16
	global_load_dword v43, v[16:17], off offset:16
	global_load_dword v42, v[20:21], off offset:3088
	global_load_dword v40, v[18:19], off offset:3088
	global_load_dword v57, v[22:23], off offset:1040
	global_load_dword v56, v[24:25], off offset:3088
	s_nop 0
	s_nop 0
	v_mov_b32_dpp v83, v130 row_ror:1 row_mask:0xf bank_mask:0xf
	v_mov_b32_dpp v86, v130 row_ror:2 row_mask:0xf bank_mask:0xf
	v_cndmask_b32_e64 v131, v83, 0, s[38:39]
	v_cndmask_b32_e64 v50, 0, v86, s[40:41]
	v_mov_b32_dpp v87, v152 row_ror:1 row_mask:0xf bank_mask:0xf
	v_mov_b32_dpp v102, v152 row_ror:2 row_mask:0xf bank_mask:0xf
	v_cndmask_b32_e64 v153, v87, 0, s[38:39]
	v_cndmask_b32_e64 v58, 0, v102, s[40:41]
	s_waitcnt vmcnt(4)
; __device__ __forceinline__ float sigmoidf_(float x) { return __builtin_amdgcn_rcpf(1.0f + __expf(-x)); }
; template <int N> __device__ __forceinline__ float dpp_ror(float v) { return __builtin_bit_cast(float, __builtin_amdgcn_update_dpp(0, __builtin_bit_cast(int, v), 0x120 + N, 0xf, 0xf, false)); }
;     __device__ __forceinline__ void operator()(Acc& acc, const Unit& u, int wr, int wc, int fr, int fq) const {
;     ...
;             for (int i = 0; i < 4; ++i) {
;                 const int cg_ = ch0 + 4 * n + i, cv_ = DFF + cg_;
;                 const float g0 = cw[cg_], g1 = cw[NUP + cg_], g2 = cw[2 * NUP + cg_], gb = cb[cg_];
;                 const float v0 = cw[cv_], v1 = cw[NUP + cv_], v2 = cw[2 * NUP + cv_], vb = cb[cv_];
;                 float pg1 = 0.f, pg2 = 0.f, pv1 = 0.f, pv2 = 0.f;
; #pragma unroll
;                 for (int q = 0; q < 8; ++q) {
;                     float cgv = acc[q >> 2][0][q & 3][n][i], cvv = acc[q >> 2][1][q & 3][n][i];
;                     asm volatile("" : "+v"(cgv), "+v"(cvv) : "v"(chain));
;                     const float tg1 = dpp_ror<1>(cgv), tg2 = dpp_ror<2>(cgv), tv1 = dpp_ror<1>(cvv), tv2 = dpp_ror<2>(cvv);
;                     const float sg1 = fr >= 1 ? tg1 : pg1, sg2 = fr >= 2 ? tg2 : pg2, sv1 = fr >= 1 ? tv1 : pv1, sv2 = fr >= 2 ? tv2 : pv2;
;                     const float gg = gb + g0 * sg2 + g1 * sg1 + g2 * cgv;
;                     const float vv = vb + v0 * sv2 + v1 * sv1 + v2 * cvv;
;                     chain = gg * sigmoidf_(gg) * vv; acc[q >> 2][0][q & 3][n][i] = chain;
;                     pg1 = tg1; pg2 = tg2; pv1 = tv1; pv2 = tv2;
;                 }
	v_fma_f32 v59, v41, v50, v43
	v_pk_mul_f32 v[50:51], v[38:39], v[130:131]
	s_waitcnt vmcnt(2)
	v_fma_f32 v121, v40, v58, v42
	v_add_f32_e32 v51, v51, v59
	v_add_f32_e32 v123, v50, v51
	v_mul_f32_e32 v50, 0xbfb8aa3b, v123
	v_exp_f32_e32 v125, v50
	v_mov_b32_e32 v51, v38
	s_waitcnt vmcnt(0)
	v_pk_mul_f32 v[58:59], v[56:57], v[152:153]
	v_mov_b32_e32 v50, v56
	v_add_f32_e32 v38, 1.0, v125
	v_rcp_f32_e32 v56, v38
	v_mov_b32_e32 v38, v57
	v_add_f32_e32 v57, v59, v121
	v_add_f32_e32 v57, v58, v57
	v_mul_f32_e32 v56, v123, v56
	v_mul_f32_e32 v56, v57, v56
	s_nop 1
	v_mov_b32_dpp v105, v119 row_ror:2 row_mask:0xf bank_mask:0xf
	v_mov_b32_dpp v111, v118 row_ror:1 row_mask:0xf bank_mask:0xf
	v_mov_b32_dpp v115, v118 row_ror:2 row_mask:0xf bank_mask:0xf
	v_mov_b32_dpp v103, v119 row_ror:1 row_mask:0xf bank_mask:0xf
	v_cndmask_b32_e64 v58, v111, v87, s[38:39]
	v_cndmask_b32_e64 v87, v86, v105, s[40:41]
	v_cndmask_b32_e64 v86, v102, v115, s[40:41]
	v_cndmask_b32_e64 v59, v103, v83, s[38:39]
	v_pk_fma_f32 v[86:87], v[40:41], v[86:87], v[42:43]
	v_pk_fma_f32 v[58:59], v[38:39], v[58:59], v[86:87]
	v_pk_fma_f32 v[58:59], v[50:51], v[118:119], v[58:59]
	v_mul_f32_e32 v57, 0xbfb8aa3b, v59
	v_exp_f32_e32 v57, v57
	s_nop 0
	v_add_f32_e32 v57, 1.0, v57
	v_rcp_f32_e32 v57, v57
	s_nop 0
	v_mul_f32_e32 v57, v59, v57
	v_mul_f32_e32 v57, v58, v57
	s_nop 1
	v_mov_b32_dpp v102, v101 row_ror:2 row_mask:0xf bank_mask:0xf
	v_mov_b32_dpp v119, v100 row_ror:2 row_mask:0xf bank_mask:0xf
	v_mov_b32_dpp v83, v101 row_ror:1 row_mask:0xf bank_mask:0xf
	v_mov_b32_dpp v118, v100 row_ror:1 row_mask:0xf bank_mask:0xf
	v_cndmask_b32_e64 v87, v105, v102, s[40:41]
	v_cndmask_b32_e64 v86, v115, v119, s[40:41]
	v_cndmask_b32_e64 v59, v83, v103, s[38:39]
	v_cndmask_b32_e64 v58, v118, v111, s[38:39]
	v_pk_fma_f32 v[86:87], v[40:41], v[86:87], v[42:43]
	v_pk_fma_f32 v[58:59], v[38:39], v[58:59], v[86:87]
	v_pk_fma_f32 v[58:59], v[50:51], v[100:101], v[58:59]
	v_mul_f32_e32 v86, 0xbfb8aa3b, v59
	v_exp_f32_e32 v86, v86
	s_nop 0
	v_add_f32_e32 v86, 1.0, v86
	v_rcp_f32_e32 v86, v86
	s_nop 0
	v_mul_f32_e32 v59, v59, v86
	v_mul_f32_e32 v58, v58, v59
	s_nop 1
	v_mov_b32_dpp v105, v85 row_ror:2 row_mask:0xf bank_mask:0xf
	v_mov_b32_dpp v115, v84 row_ror:2 row_mask:0xf bank_mask:0xf
	v_mov_b32_dpp v103, v85 row_ror:1 row_mask:0xf bank_mask:0xf
	v_mov_b32_dpp v111, v84 row_ror:1 row_mask:0xf bank_mask:0xf
	v_cndmask_b32_e64 v101, v102, v105, s[40:41]
	v_cndmask_b32_e64 v100, v119, v115, s[40:41]
	v_cndmask_b32_e64 v87, v103, v83, s[38:39]
	v_cndmask_b32_e64 v86, v111, v118, s[38:39]
	v_pk_fma_f32 v[100:101], v[40:41], v[100:101], v[42:43]
	v_pk_fma_f32 v[86:87], v[38:39], v[86:87], v[100:101]
	v_pk_fma_f32 v[84:85], v[50:51], v[84:85], v[86:87]
	v_mul_f32_e32 v59, 0xbfb8aa3b, v85
	v_exp_f32_e32 v59, v59
	s_nop 0
	v_add_f32_e32 v59, 1.0, v59
	v_rcp_f32_e32 v59, v59
	s_nop 0
	v_mul_f32_e32 v59, v85, v59
	v_mul_f32_e32 v59, v84, v59
	s_nop 1
	v_mov_b32_dpp v100, v69 row_ror:2 row_mask:0xf bank_mask:0xf
	v_mov_b32_dpp v102, v68 row_ror:2 row_mask:0xf bank_mask:0xf
	v_mov_b32_dpp v83, v69 row_ror:1 row_mask:0xf bank_mask:0xf
	v_mov_b32_dpp v101, v68 row_ror:1 row_mask:0xf bank_mask:0xf
	v_cndmask_b32_e64 v87, v105, v100, s[40:41]
	v_cndmask_b32_e64 v86, v115, v102, s[40:41]
	v_cndmask_b32_e64 v85, v83, v103, s[38:39]
	v_cndmask_b32_e64 v84, v101, v111, s[38:39]
	v_pk_fma_f32 v[86:87], v[40:41], v[86:87], v[42:43]
	v_pk_fma_f32 v[84:85], v[38:39], v[84:85], v[86:87]
	v_pk_fma_f32 v[68:69], v[50:51], v[68:69], v[84:85]
	v_mul_f32_e32 v84, 0xbfb8aa3b, v69
	v_exp_f32_e32 v84, v84
	s_nop 0
	v_add_f32_e32 v84, 1.0, v84
	v_rcp_f32_e32 v84, v84
	s_nop 0
	v_mul_f32_e32 v69, v69, v84
	v_mul_f32_e32 v68, v68, v69
	s_nop 1
	v_mov_b32_dpp v105, v53 row_ror:2 row_mask:0xf bank_mask:0xf
	v_mov_b32_dpp v115, v52 row_ror:2 row_mask:0xf bank_mask:0xf
	v_mov_b32_dpp v103, v53 row_ror:1 row_mask:0xf bank_mask:0xf
	v_mov_b32_dpp v111, v52 row_ror:1 row_mask:0xf bank_mask:0xf
	v_cndmask_b32_e64 v87, v100, v105, s[40:41]
	v_cndmask_b32_e64 v86, v102, v115, s[40:41]
	v_cndmask_b32_e64 v85, v103, v83, s[38:39]
	v_cndmask_b32_e64 v84, v111, v101, s[38:39]
	v_pk_fma_f32 v[86:87], v[40:41], v[86:87], v[42:43]
	v_pk_fma_f32 v[84:85], v[38:39], v[84:85], v[86:87]
	v_pk_fma_f32 v[52:53], v[50:51], v[52:53], v[84:85]
	v_mul_f32_e32 v69, 0xbfb8aa3b, v53
	v_exp_f32_e32 v69, v69
	s_nop 0
	v_add_f32_e32 v69, 1.0, v69
	v_rcp_f32_e32 v69, v69
	s_nop 0
	v_mul_f32_e32 v53, v53, v69
	v_mul_f32_e32 v52, v52, v53
	s_nop 0
	s_nop 0
	v_mov_b32_dpp v100, v37 row_ror:2 row_mask:0xf bank_mask:0xf
	v_mov_b32_dpp v102, v36 row_ror:2 row_mask:0xf bank_mask:0xf
	v_mov_b32_dpp v83, v37 row_ror:1 row_mask:0xf bank_mask:0xf
	v_mov_b32_dpp v101, v36 row_ror:1 row_mask:0xf bank_mask:0xf
	v_cndmask_b32_e64 v87, v105, v100, s[40:41]
	v_cndmask_b32_e64 v86, v115, v102, s[40:41]
	v_cndmask_b32_e64 v85, v83, v103, s[38:39]
	v_cndmask_b32_e64 v84, v101, v111, s[38:39]
	v_pk_fma_f32 v[86:87], v[40:41], v[86:87], v[42:43]
	s_nop 0
	v_pk_fma_f32 v[84:85], v[38:39], v[84:85], v[86:87]
	v_pk_fma_f32 v[36:37], v[50:51], v[36:37], v[84:85]
	v_mul_f32_e32 v53, 0xbfb8aa3b, v37
	v_exp_f32_e32 v53, v53
	s_nop 0
	v_add_f32_e32 v53, 1.0, v53
	v_rcp_f32_e32 v53, v53
	s_nop 0
	v_mul_f32_e32 v37, v37, v53
	v_mul_f32_e32 v53, v36, v37
	s_nop 1
	v_mov_b32_dpp v84, v35 row_ror:2 row_mask:0xf bank_mask:0xf
	v_mov_b32_dpp v85, v34 row_ror:1 row_mask:0xf bank_mask:0xf
	v_mov_b32_dpp v86, v34 row_ror:2 row_mask:0xf bank_mask:0xf
	v_mov_b32_dpp v69, v35 row_ror:1 row_mask:0xf bank_mask:0xf
	v_cndmask_b32_e64 v36, v85, v101, s[38:39]
	v_cndmask_b32_e64 v85, v100, v84, s[40:41]
	v_cndmask_b32_e64 v84, v102, v86, s[40:41]
	v_cndmask_b32_e64 v37, v69, v83, s[38:39]
	v_pk_fma_f32 v[40:41], v[40:41], v[84:85], v[42:43]
	s_nop 0
	v_pk_fma_f32 v[36:37], v[38:39], v[36:37], v[40:41]
	s_nop 0
	v_pk_fma_f32 v[34:35], v[50:51], v[34:35], v[36:37]
	s_nop 0
	v_mul_f32_e32 v36, 0xbfb8aa3b, v35
	v_exp_f32_e32 v36, v36
	s_nop 0
	v_add_f32_e32 v36, 1.0, v36
	v_rcp_f32_e32 v36, v36
	s_nop 0
	v_mul_f32_e32 v35, v35, v36
	v_mul_f32_e32 v42, v34, v35
	global_load_dword v37, v[6:7], off offset:20
	global_load_dword v35, v[8:9], off offset:2068
	global_load_dword v34, v[10:11], off offset:20
	global_load_dword v39, v[16:17], off offset:20
	global_load_dword v38, v[20:21], off offset:3092
	global_load_dword v36, v[18:19], off offset:3092
	global_load_dword v51, v[22:23], off offset:1044
	global_load_dword v50, v[24:25], off offset:3092
	s_nop 0
	s_nop 0
	v_mov_b32_dpp v69, v126 row_ror:1 row_mask:0xf bank_mask:0xf
	v_mov_b32_dpp v83, v126 row_ror:2 row_mask:0xf bank_mask:0xf
	v_cndmask_b32_e64 v127, v69, 0, s[38:39]
	v_cndmask_b32_e64 v40, 0, v83, s[40:41]
	v_mov_b32_dpp v86, v128 row_ror:1 row_mask:0xf bank_mask:0xf
	v_cndmask_b32_e64 v129, v86, 0, s[38:39]
	v_mov_b32_dpp v87, v128 row_ror:2 row_mask:0xf bank_mask:0xf
	v_cndmask_b32_e64 v43, 0, v87, s[40:41]
	s_waitcnt vmcnt(4)
; __device__ __forceinline__ float sigmoidf_(float x) { return __builtin_amdgcn_rcpf(1.0f + __expf(-x)); }
; template <int N> __device__ __forceinline__ float dpp_ror(float v) { return __builtin_bit_cast(float, __builtin_amdgcn_update_dpp(0, __builtin_bit_cast(int, v), 0x120 + N, 0xf, 0xf, false)); }
;     __device__ __forceinline__ void operator()(Acc& acc, const Unit& u, int wr, int wc, int fr, int fq) const {
;     ...
;             for (int i = 0; i < 4; ++i) {
;                 const int cg_ = ch0 + 4 * n + i, cv_ = DFF + cg_;
;                 const float g0 = cw[cg_], g1 = cw[NUP + cg_], g2 = cw[2 * NUP + cg_], gb = cb[cg_];
;                 const float v0 = cw[cv_], v1 = cw[NUP + cv_], v2 = cw[2 * NUP + cv_], vb = cb[cv_];
;                 float pg1 = 0.f, pg2 = 0.f, pv1 = 0.f, pv2 = 0.f;
; #pragma unroll
;                 for (int q = 0; q < 8; ++q) {
;                     float cgv = acc[q >> 2][0][q & 3][n][i], cvv = acc[q >> 2][1][q & 3][n][i];
;                     asm volatile("" : "+v"(cgv), "+v"(cvv) : "v"(chain));
;                     const float tg1 = dpp_ror<1>(cgv), tg2 = dpp_ror<2>(cgv), tv1 = dpp_ror<1>(cvv), tv2 = dpp_ror<2>(cvv);
;                     const float sg1 = fr >= 1 ? tg1 : pg1, sg2 = fr >= 2 ? tg2 : pg2, sv1 = fr >= 1 ? tv1 : pv1, sv2 = fr >= 2 ? tv2 : pv2;
;                     const float gg = gb + g0 * sg2 + g1 * sg1 + g2 * cgv;
;                     const float vv = vb + v0 * sv2 + v1 * sv1 + v2 * cvv;
;                     chain = gg * sigmoidf_(gg) * vv; acc[q >> 2][0][q & 3][n][i] = chain;
;                     pg1 = tg1; pg2 = tg2; pv1 = tv1; pv2 = tv2;
;                 }
	v_fma_f32 v84, v37, v40, v39
	v_pk_mul_f32 v[40:41], v[34:35], v[126:127]
	s_waitcnt vmcnt(2)
	v_fma_f32 v43, v36, v43, v38
	v_add_f32_e32 v41, v41, v84
	v_add_f32_e32 v105, v40, v41
	v_mul_f32_e32 v40, 0xbfb8aa3b, v105
	v_exp_f32_e32 v111, v40
	v_mov_b32_e32 v41, v34
	s_waitcnt vmcnt(0)
	v_pk_mul_f32 v[84:85], v[50:51], v[128:129]
	v_mov_b32_e32 v40, v50
	v_add_f32_e32 v34, 1.0, v111
	v_rcp_f32_e32 v50, v34
	v_add_f32_e32 v43, v85, v43
	v_add_f32_e32 v43, v84, v43
	v_mov_b32_e32 v34, v51
	v_mul_f32_e32 v50, v105, v50
	v_mul_f32_e32 v43, v43, v50
	s_nop 0
	s_nop 0
	v_mov_b32_dpp v101, v117 row_ror:2 row_mask:0xf bank_mask:0xf
	v_mov_b32_dpp v103, v116 row_ror:2 row_mask:0xf bank_mask:0xf
	v_mov_b32_dpp v100, v117 row_ror:1 row_mask:0xf bank_mask:0xf
	v_mov_b32_dpp v102, v116 row_ror:1 row_mask:0xf bank_mask:0xf
	v_cndmask_b32_e64 v85, v83, v101, s[40:41]
	v_cndmask_b32_e64 v84, v87, v103, s[40:41]
	v_cndmask_b32_e64 v51, v100, v69, s[38:39]
	v_cndmask_b32_e64 v50, v102, v86, s[38:39]
	v_pk_fma_f32 v[84:85], v[36:37], v[84:85], v[38:39]
	v_pk_fma_f32 v[50:51], v[34:35], v[50:51], v[84:85]
	s_nop 0
	v_pk_fma_f32 v[50:51], v[40:41], v[116:117], v[50:51]
	s_nop 0
	v_mul_f32_e32 v69, 0xbfb8aa3b, v51
	v_exp_f32_e32 v69, v69
	s_nop 0
	v_add_f32_e32 v69, 1.0, v69
	v_rcp_f32_e32 v69, v69
	s_nop 0
	v_mul_f32_e32 v51, v51, v69
	v_mul_f32_e32 v50, v50, v51
	s_nop 1
	v_mov_b32_dpp v105, v97 row_ror:2 row_mask:0xf bank_mask:0xf
	v_mov_b32_dpp v115, v96 row_ror:2 row_mask:0xf bank_mask:0xf
	v_mov_b32_dpp v83, v97 row_ror:1 row_mask:0xf bank_mask:0xf
	v_mov_b32_dpp v111, v96 row_ror:1 row_mask:0xf bank_mask:0xf
	v_cndmask_b32_e64 v87, v101, v105, s[40:41]
	v_cndmask_b32_e64 v86, v103, v115, s[40:41]
	v_cndmask_b32_e64 v85, v83, v100, s[38:39]
	v_cndmask_b32_e64 v84, v111, v102, s[38:39]
	v_pk_fma_f32 v[86:87], v[36:37], v[86:87], v[38:39]
	v_pk_fma_f32 v[84:85], v[34:35], v[84:85], v[86:87]
	v_pk_fma_f32 v[84:85], v[40:41], v[96:97], v[84:85]
	v_mul_f32_e32 v51, 0xbfb8aa3b, v85
	v_exp_f32_e32 v51, v51
	s_nop 0
	v_add_f32_e32 v51, 1.0, v51
	v_rcp_f32_e32 v51, v51
	s_nop 0
	v_mul_f32_e32 v51, v85, v51
	v_mul_f32_e32 v51, v84, v51
	s_nop 1
	v_mov_b32_dpp v97, v81 row_ror:2 row_mask:0xf bank_mask:0xf
	v_mov_b32_dpp v101, v80 row_ror:2 row_mask:0xf bank_mask:0xf
	v_mov_b32_dpp v96, v81 row_ror:1 row_mask:0xf bank_mask:0xf
	v_mov_b32_dpp v100, v80 row_ror:1 row_mask:0xf bank_mask:0xf
	v_cndmask_b32_e64 v87, v105, v97, s[40:41]
	v_cndmask_b32_e64 v86, v115, v101, s[40:41]
	v_cndmask_b32_e64 v85, v96, v83, s[38:39]
	v_cndmask_b32_e64 v84, v100, v111, s[38:39]
	v_pk_fma_f32 v[86:87], v[36:37], v[86:87], v[38:39]
	v_pk_fma_f32 v[84:85], v[34:35], v[84:85], v[86:87]
	v_pk_fma_f32 v[80:81], v[40:41], v[80:81], v[84:85]
	v_mul_f32_e32 v69, 0xbfb8aa3b, v81
	v_exp_f32_e32 v69, v69
	s_nop 0
	v_add_f32_e32 v69, 1.0, v69
	v_rcp_f32_e32 v69, v69
	s_nop 0
	v_mul_f32_e32 v69, v81, v69
	v_mul_f32_e32 v69, v80, v69
	s_nop 1
	v_mov_b32_dpp v86, v67 row_ror:2 row_mask:0xf bank_mask:0xf
	v_mov_b32_dpp v102, v66 row_ror:2 row_mask:0xf bank_mask:0xf
	v_mov_b32_dpp v83, v67 row_ror:1 row_mask:0xf bank_mask:0xf
	v_mov_b32_dpp v87, v66 row_ror:1 row_mask:0xf bank_mask:0xf
	v_cndmask_b32_e64 v85, v97, v86, s[40:41]
	v_cndmask_b32_e64 v84, v101, v102, s[40:41]
	v_cndmask_b32_e64 v81, v83, v96, s[38:39]
	v_cndmask_b32_e64 v80, v87, v100, s[38:39]
	v_pk_fma_f32 v[84:85], v[36:37], v[84:85], v[38:39]
	v_pk_fma_f32 v[80:81], v[34:35], v[80:81], v[84:85]
	v_pk_fma_f32 v[66:67], v[40:41], v[66:67], v[80:81]
	v_mul_f32_e32 v80, 0xbfb8aa3b, v67
	v_exp_f32_e32 v80, v80
	s_nop 0
	v_add_f32_e32 v80, 1.0, v80
	v_rcp_f32_e32 v80, v80
	s_nop 0
	v_mul_f32_e32 v67, v67, v80
	v_mul_f32_e32 v66, v66, v67
	s_nop 1
	v_mov_b32_dpp v97, v49 row_ror:2 row_mask:0xf bank_mask:0xf
	v_mov_b32_dpp v101, v48 row_ror:2 row_mask:0xf bank_mask:0xf
	v_mov_b32_dpp v96, v49 row_ror:1 row_mask:0xf bank_mask:0xf
	v_mov_b32_dpp v100, v48 row_ror:1 row_mask:0xf bank_mask:0xf
	v_cndmask_b32_e64 v85, v86, v97, s[40:41]
	v_cndmask_b32_e64 v84, v102, v101, s[40:41]
	v_cndmask_b32_e64 v81, v96, v83, s[38:39]
	v_cndmask_b32_e64 v80, v100, v87, s[38:39]
	v_pk_fma_f32 v[84:85], v[36:37], v[84:85], v[38:39]
	v_pk_fma_f32 v[80:81], v[34:35], v[80:81], v[84:85]
	v_pk_fma_f32 v[48:49], v[40:41], v[48:49], v[80:81]
	v_mul_f32_e32 v67, 0xbfb8aa3b, v49
	v_exp_f32_e32 v67, v67
	s_nop 0
	v_add_f32_e32 v67, 1.0, v67
	v_rcp_f32_e32 v67, v67
	s_nop 0
	v_mul_f32_e32 v49, v49, v67
	v_mul_f32_e32 v48, v48, v49
	s_nop 0
	s_nop 0
	v_mov_b32_dpp v86, v33 row_ror:2 row_mask:0xf bank_mask:0xf
	v_mov_b32_dpp v102, v32 row_ror:2 row_mask:0xf bank_mask:0xf
	v_mov_b32_dpp v83, v33 row_ror:1 row_mask:0xf bank_mask:0xf
	v_mov_b32_dpp v87, v32 row_ror:1 row_mask:0xf bank_mask:0xf
	v_cndmask_b32_e64 v85, v97, v86, s[40:41]
	v_cndmask_b32_e64 v84, v101, v102, s[40:41]
	v_cndmask_b32_e64 v81, v83, v96, s[38:39]
	v_cndmask_b32_e64 v80, v87, v100, s[38:39]
	v_pk_fma_f32 v[84:85], v[36:37], v[84:85], v[38:39]
	s_nop 0
	v_pk_fma_f32 v[80:81], v[34:35], v[80:81], v[84:85]
	v_pk_fma_f32 v[32:33], v[40:41], v[32:33], v[80:81]
	v_mul_f32_e32 v49, 0xbfb8aa3b, v33
	v_exp_f32_e32 v49, v49
	s_nop 0
	v_add_f32_e32 v49, 1.0, v49
	v_rcp_f32_e32 v49, v49
	s_nop 0
	v_mul_f32_e32 v33, v33, v49
	v_mul_f32_e32 v49, v32, v33
	s_nop 1
	v_mov_b32_dpp v80, v27 row_ror:2 row_mask:0xf bank_mask:0xf
	v_mov_b32_dpp v81, v26 row_ror:1 row_mask:0xf bank_mask:0xf
	v_mov_b32_dpp v84, v26 row_ror:2 row_mask:0xf bank_mask:0xf
	v_mov_b32_dpp v67, v27 row_ror:1 row_mask:0xf bank_mask:0xf
	v_cndmask_b32_e64 v32, v81, v87, s[38:39]
	v_cndmask_b32_e64 v81, v86, v80, s[40:41]
	v_cndmask_b32_e64 v80, v102, v84, s[40:41]
	v_cndmask_b32_e64 v33, v67, v83, s[38:39]
	v_pk_fma_f32 v[36:37], v[36:37], v[80:81], v[38:39]
	s_nop 0
	v_pk_fma_f32 v[32:33], v[34:35], v[32:33], v[36:37]
	s_nop 0
	v_pk_fma_f32 v[26:27], v[40:41], v[26:27], v[32:33]
	s_nop 0
	v_mul_f32_e32 v32, 0xbfb8aa3b, v27
	v_exp_f32_e32 v32, v32
	s_nop 0
	v_add_f32_e32 v32, 1.0, v32
	v_rcp_f32_e32 v32, v32
	s_nop 0
	v_mul_f32_e32 v27, v27, v32
	v_mul_f32_e32 v38, v26, v27
	global_load_dword v33, v[6:7], off offset:24
	global_load_dword v27, v[8:9], off offset:2072
	global_load_dword v26, v[10:11], off offset:24
	global_load_dword v35, v[16:17], off offset:24
	global_load_dword v34, v[20:21], off offset:3096
	global_load_dword v32, v[18:19], off offset:3096
	global_load_dword v41, v[22:23], off offset:1048
	global_load_dword v40, v[24:25], off offset:3096
	s_nop 0
	s_nop 0
	v_mov_b32_dpp v67, v122 row_ror:1 row_mask:0xf bank_mask:0xf
	v_mov_b32_dpp v83, v122 row_ror:2 row_mask:0xf bank_mask:0xf
	v_cndmask_b32_e64 v123, v67, 0, s[38:39]
	v_cndmask_b32_e64 v36, 0, v83, s[40:41]
	v_mov_b32_dpp v84, v124 row_ror:1 row_mask:0xf bank_mask:0xf
	v_cndmask_b32_e64 v125, v84, 0, s[38:39]
	v_mov_b32_dpp v85, v124 row_ror:2 row_mask:0xf bank_mask:0xf
	v_cndmask_b32_e64 v39, 0, v85, s[40:41]
	s_waitcnt vmcnt(4)
; __device__ __forceinline__ float sigmoidf_(float x) { return __builtin_amdgcn_rcpf(1.0f + __expf(-x)); }
; template <int N> __device__ __forceinline__ float dpp_ror(float v) { return __builtin_bit_cast(float, __builtin_amdgcn_update_dpp(0, __builtin_bit_cast(int, v), 0x120 + N, 0xf, 0xf, false)); }
;     __device__ __forceinline__ void operator()(Acc& acc, const Unit& u, int wr, int wc, int fr, int fq) const {
;     ...
;             for (int i = 0; i < 4; ++i) {
;                 const int cg_ = ch0 + 4 * n + i, cv_ = DFF + cg_;
;                 const float g0 = cw[cg_], g1 = cw[NUP + cg_], g2 = cw[2 * NUP + cg_], gb = cb[cg_];
;                 const float v0 = cw[cv_], v1 = cw[NUP + cv_], v2 = cw[2 * NUP + cv_], vb = cb[cv_];
;                 float pg1 = 0.f, pg2 = 0.f, pv1 = 0.f, pv2 = 0.f;
; #pragma unroll
;                 for (int q = 0; q < 8; ++q) {
;                     float cgv = acc[q >> 2][0][q & 3][n][i], cvv = acc[q >> 2][1][q & 3][n][i];
;                     asm volatile("" : "+v"(cgv), "+v"(cvv) : "v"(chain));
;                     const float tg1 = dpp_ror<1>(cgv), tg2 = dpp_ror<2>(cgv), tv1 = dpp_ror<1>(cvv), tv2 = dpp_ror<2>(cvv);
;                     const float sg1 = fr >= 1 ? tg1 : pg1, sg2 = fr >= 2 ? tg2 : pg2, sv1 = fr >= 1 ? tv1 : pv1, sv2 = fr >= 2 ? tv2 : pv2;
;                     const float gg = gb + g0 * sg2 + g1 * sg1 + g2 * cgv;
;                     const float vv = vb + v0 * sv2 + v1 * sv1 + v2 * cvv;
;                     chain = gg * sigmoidf_(gg) * vv; acc[q >> 2][0][q & 3][n][i] = chain;
;                     pg1 = tg1; pg2 = tg2; pv1 = tv1; pv2 = tv2;
;                 }
	v_fma_f32 v80, v33, v36, v35
	v_pk_mul_f32 v[36:37], v[26:27], v[122:123]
	s_waitcnt vmcnt(2)
	v_fma_f32 v39, v32, v39, v34
	v_add_f32_e32 v37, v37, v80
	v_add_f32_e32 v100, v36, v37
	v_mul_f32_e32 v36, 0xbfb8aa3b, v100
	v_exp_f32_e32 v101, v36
	v_mov_b32_e32 v37, v26
	s_waitcnt vmcnt(0)
	v_pk_mul_f32 v[80:81], v[40:41], v[124:125]
	v_mov_b32_e32 v36, v40
	v_add_f32_e32 v26, 1.0, v101
	v_rcp_f32_e32 v40, v26
	v_add_f32_e32 v39, v81, v39
	v_add_f32_e32 v39, v80, v39
	v_mov_b32_e32 v26, v41
	v_mul_f32_e32 v40, v100, v40
	v_mul_f32_e32 v39, v39, v40
	s_nop 0
	s_nop 0
	v_mov_b32_dpp v87, v113 row_ror:2 row_mask:0xf bank_mask:0xf
	v_mov_b32_dpp v97, v112 row_ror:2 row_mask:0xf bank_mask:0xf
	v_mov_b32_dpp v86, v113 row_ror:1 row_mask:0xf bank_mask:0xf
	v_mov_b32_dpp v96, v112 row_ror:1 row_mask:0xf bank_mask:0xf
	v_cndmask_b32_e64 v81, v83, v87, s[40:41]
	v_cndmask_b32_e64 v80, v85, v97, s[40:41]
	v_cndmask_b32_e64 v41, v86, v67, s[38:39]
	v_cndmask_b32_e64 v40, v96, v84, s[38:39]
	v_pk_fma_f32 v[80:81], v[32:33], v[80:81], v[34:35]
	v_pk_fma_f32 v[40:41], v[26:27], v[40:41], v[80:81]
	s_nop 0
	v_pk_fma_f32 v[40:41], v[36:37], v[112:113], v[40:41]
	s_nop 0
	v_mul_f32_e32 v67, 0xbfb8aa3b, v41
	v_exp_f32_e32 v67, v67
	s_nop 0
	v_add_f32_e32 v67, 1.0, v67
	v_rcp_f32_e32 v67, v67
	s_nop 0
	v_mul_f32_e32 v41, v41, v67
	v_mul_f32_e32 v40, v40, v41
	s_nop 1
	v_mov_b32_dpp v100, v95 row_ror:2 row_mask:0xf bank_mask:0xf
	v_mov_b32_dpp v102, v94 row_ror:2 row_mask:0xf bank_mask:0xf
	v_mov_b32_dpp v83, v95 row_ror:1 row_mask:0xf bank_mask:0xf
	v_mov_b32_dpp v101, v94 row_ror:1 row_mask:0xf bank_mask:0xf
	v_cndmask_b32_e64 v85, v87, v100, s[40:41]
	v_cndmask_b32_e64 v84, v97, v102, s[40:41]
	v_cndmask_b32_e64 v81, v83, v86, s[38:39]
	v_cndmask_b32_e64 v80, v101, v96, s[38:39]
	v_pk_fma_f32 v[84:85], v[32:33], v[84:85], v[34:35]
	v_pk_fma_f32 v[80:81], v[26:27], v[80:81], v[84:85]
	v_pk_fma_f32 v[80:81], v[36:37], v[94:95], v[80:81]
	v_mul_f32_e32 v41, 0xbfb8aa3b, v81
	v_exp_f32_e32 v41, v41
	s_nop 0
	v_add_f32_e32 v41, 1.0, v41
	v_rcp_f32_e32 v41, v41
	s_nop 0
	v_mul_f32_e32 v41, v81, v41
	v_mul_f32_e32 v41, v80, v41
	s_nop 1
	v_mov_b32_dpp v87, v79 row_ror:2 row_mask:0xf bank_mask:0xf
	v_mov_b32_dpp v95, v78 row_ror:2 row_mask:0xf bank_mask:0xf
	v_mov_b32_dpp v86, v79 row_ror:1 row_mask:0xf bank_mask:0xf
	v_mov_b32_dpp v94, v78 row_ror:1 row_mask:0xf bank_mask:0xf
	v_cndmask_b32_e64 v85, v100, v87, s[40:41]
	v_cndmask_b32_e64 v84, v102, v95, s[40:41]
	v_cndmask_b32_e64 v81, v86, v83, s[38:39]
	v_cndmask_b32_e64 v80, v94, v101, s[38:39]
	v_pk_fma_f32 v[84:85], v[32:33], v[84:85], v[34:35]
	v_pk_fma_f32 v[80:81], v[26:27], v[80:81], v[84:85]
	v_pk_fma_f32 v[78:79], v[36:37], v[78:79], v[80:81]
	v_mul_f32_e32 v67, 0xbfb8aa3b, v79
	v_exp_f32_e32 v67, v67
	s_nop 0
	v_add_f32_e32 v67, 1.0, v67
	v_rcp_f32_e32 v67, v67
	s_nop 0
	v_mul_f32_e32 v67, v79, v67
	v_mul_f32_e32 v67, v78, v67
	s_nop 1
	v_mov_b32_dpp v84, v65 row_ror:2 row_mask:0xf bank_mask:0xf
	v_mov_b32_dpp v96, v64 row_ror:2 row_mask:0xf bank_mask:0xf
	v_mov_b32_dpp v83, v65 row_ror:1 row_mask:0xf bank_mask:0xf
	v_mov_b32_dpp v85, v64 row_ror:1 row_mask:0xf bank_mask:0xf
	v_cndmask_b32_e64 v81, v87, v84, s[40:41]
	v_cndmask_b32_e64 v80, v95, v96, s[40:41]
	v_cndmask_b32_e64 v79, v83, v86, s[38:39]
	v_cndmask_b32_e64 v78, v85, v94, s[38:39]
	v_pk_fma_f32 v[80:81], v[32:33], v[80:81], v[34:35]
	v_pk_fma_f32 v[78:79], v[26:27], v[78:79], v[80:81]
	v_pk_fma_f32 v[64:65], v[36:37], v[64:65], v[78:79]
	v_mul_f32_e32 v78, 0xbfb8aa3b, v65
	v_exp_f32_e32 v78, v78
	s_nop 0
	v_add_f32_e32 v78, 1.0, v78
	v_rcp_f32_e32 v78, v78
	s_nop 0
	v_mul_f32_e32 v65, v65, v78
	v_mul_f32_e32 v64, v64, v65
	s_nop 1
	v_mov_b32_dpp v87, v47 row_ror:2 row_mask:0xf bank_mask:0xf
	v_mov_b32_dpp v95, v46 row_ror:2 row_mask:0xf bank_mask:0xf
	v_mov_b32_dpp v86, v47 row_ror:1 row_mask:0xf bank_mask:0xf
	v_mov_b32_dpp v94, v46 row_ror:1 row_mask:0xf bank_mask:0xf
	v_cndmask_b32_e64 v81, v84, v87, s[40:41]
	v_cndmask_b32_e64 v80, v96, v95, s[40:41]
	v_cndmask_b32_e64 v79, v86, v83, s[38:39]
	v_cndmask_b32_e64 v78, v94, v85, s[38:39]
	v_pk_fma_f32 v[80:81], v[32:33], v[80:81], v[34:35]
	v_pk_fma_f32 v[78:79], v[26:27], v[78:79], v[80:81]
	v_pk_fma_f32 v[46:47], v[36:37], v[46:47], v[78:79]
	v_mul_f32_e32 v65, 0xbfb8aa3b, v47
	v_exp_f32_e32 v65, v65
	s_nop 0
	v_add_f32_e32 v65, 1.0, v65
	v_rcp_f32_e32 v65, v65
	s_nop 0
	v_mul_f32_e32 v47, v47, v65
	v_mul_f32_e32 v46, v46, v47
	s_nop 0
	s_nop 0
	v_mov_b32_dpp v84, v31 row_ror:2 row_mask:0xf bank_mask:0xf
	v_mov_b32_dpp v96, v30 row_ror:2 row_mask:0xf bank_mask:0xf
	v_mov_b32_dpp v83, v31 row_ror:1 row_mask:0xf bank_mask:0xf
	v_mov_b32_dpp v85, v30 row_ror:1 row_mask:0xf bank_mask:0xf
	v_cndmask_b32_e64 v81, v87, v84, s[40:41]
	v_cndmask_b32_e64 v80, v95, v96, s[40:41]
	v_cndmask_b32_e64 v79, v83, v86, s[38:39]
	v_cndmask_b32_e64 v78, v85, v94, s[38:39]
	v_pk_fma_f32 v[80:81], v[32:33], v[80:81], v[34:35]
	v_pk_fma_f32 v[78:79], v[26:27], v[78:79], v[80:81]
	v_pk_fma_f32 v[30:31], v[36:37], v[30:31], v[78:79]
	v_mul_f32_e32 v47, 0xbfb8aa3b, v31
	v_exp_f32_e32 v47, v47
	s_nop 0
	v_add_f32_e32 v47, 1.0, v47
	v_rcp_f32_e32 v47, v47
	s_nop 0
	v_mul_f32_e32 v31, v31, v47
	v_mul_f32_e32 v30, v30, v31
	s_nop 1
	v_mov_b32_dpp v80, v15 row_ror:2 row_mask:0xf bank_mask:0xf
	v_mov_b32_dpp v86, v14 row_ror:2 row_mask:0xf bank_mask:0xf
	v_mov_b32_dpp v65, v15 row_ror:1 row_mask:0xf bank_mask:0xf
	v_mov_b32_dpp v78, v14 row_ror:1 row_mask:0xf bank_mask:0xf
	v_cndmask_b32_e64 v81, v84, v80, s[40:41]
	v_cndmask_b32_e64 v80, v96, v86, s[40:41]
	v_cndmask_b32_e64 v79, v65, v83, s[38:39]
	v_cndmask_b32_e64 v78, v78, v85, s[38:39]
	v_pk_fma_f32 v[32:33], v[32:33], v[80:81], v[34:35]
	s_nop 0
	v_pk_fma_f32 v[26:27], v[26:27], v[78:79], v[32:33]
	s_nop 0
	v_pk_fma_f32 v[14:15], v[36:37], v[14:15], v[26:27]
	s_nop 0
	v_mul_f32_e32 v26, 0xbfb8aa3b, v15
	v_exp_f32_e32 v26, v26
	s_nop 0
	v_add_f32_e32 v26, 1.0, v26
	v_rcp_f32_e32 v26, v26
	s_nop 0
	v_mul_f32_e32 v15, v15, v26
	v_mul_f32_e32 v26, v14, v15
	global_load_dword v15, v[6:7], off offset:28
	s_nop 0
	global_load_dword v7, v[8:9], off offset:2076
	global_load_dword v6, v[10:11], off offset:28
	s_nop 0
	global_load_dword v9, v[16:17], off offset:28
	global_load_dword v14, v[18:19], off offset:3100
	s_nop 0
	global_load_dword v17, v[22:23], off offset:1052
	global_load_dword v16, v[24:25], off offset:3100
	global_load_dword v8, v[20:21], off offset:3100
	s_nop 0
	s_nop 0
	v_mov_b32_dpp v19, v120 row_ror:1 row_mask:0xf bank_mask:0xf
	v_mov_b32_dpp v22, v120 row_ror:2 row_mask:0xf bank_mask:0xf
	v_cndmask_b32_e64 v121, v19, 0, s[38:39]
	v_cndmask_b32_e64 v10, 0, v22, s[40:41]
	v_mov_b32_dpp v20, v110 row_ror:1 row_mask:0xf bank_mask:0xf
	v_mov_b32_dpp v24, v110 row_ror:2 row_mask:0xf bank_mask:0xf
	v_cndmask_b32_e64 v111, v20, 0, s[38:39]
	v_cndmask_b32_e64 v18, 0, v24, s[40:41]
	v_mov_b32_e32 v35, v3
	v_mov_b32_e32 v36, v3
	s_waitcnt vmcnt(4)
; __device__ __forceinline__ unsigned pk2(float lo, float hi) { const f32x2_t v = {lo, hi}; const bf16x2_t b = __builtin_convertvector(v, bf16x2_t); return __builtin_bit_cast(unsigned, b); }
; __device__ __forceinline__ float sigmoidf_(float x) { return __builtin_amdgcn_rcpf(1.0f + __expf(-x)); }
; template <int N> __device__ __forceinline__ float dpp_ror(float v) { return __builtin_bit_cast(float, __builtin_amdgcn_update_dpp(0, __builtin_bit_cast(int, v), 0x120 + N, 0xf, 0xf, false)); }
;     __device__ __forceinline__ void operator()(Acc& acc, const Unit& u, int wr, int wc, int fr, int fq) const {
;     ...
;                 for (int q = 0; q < 8; ++q) {
;                     float cgv = acc[q >> 2][0][q & 3][n][i], cvv = acc[q >> 2][1][q & 3][n][i];
;                     asm volatile("" : "+v"(cgv), "+v"(cvv) : "v"(chain));
;                     const float tg1 = dpp_ror<1>(cgv), tg2 = dpp_ror<2>(cgv), tv1 = dpp_ror<1>(cvv), tv2 = dpp_ror<2>(cvv);
;                     const float sg1 = fr >= 1 ? tg1 : pg1, sg2 = fr >= 2 ? tg2 : pg2, sv1 = fr >= 1 ? tv1 : pv1, sv2 = fr >= 2 ? tv2 : pv2;
;                     const float gg = gb + g0 * sg2 + g1 * sg1 + g2 * cgv;
;                     const float vv = vb + v0 * sv2 + v1 * sv1 + v2 * cvv;
;                     chain = gg * sigmoidf_(gg) * vv; acc[q >> 2][0][q & 3][n][i] = chain;
;                     pg1 = tg1; pg2 = tg2; pv1 = tv1; pv2 = tv2;
;                 }
;                 __builtin_amdgcn_sched_barrier(0);
;             }
;         }
; #pragma unroll
;         for (int q = 0; q < 8; ++q) {
;             const int t = tbase + 16 * q;
;             if ((16 * q + fr >= 2) && (t < SEQ)) {
;                 const f32x4 a0 = acc[q >> 2][0][q & 3][0], a1 = acc[q >> 2][0][q & 3][1];
;                 u32x4 w; w.x = pk2(a0[0], a0[1]); w.y = pk2(a0[2], a0[3]); w.z = pk2(a1[0], a1[1]); w.w = pk2(a1[2], a1[3]);
;                 *(u32x4*)(act + (size_t)(b * SEQ + t) * DFF + ch0) = w;
;             }
;         }
	v_fma_f32 v21, v15, v10, v9
	v_pk_mul_f32 v[10:11], v[6:7], v[120:121]
	s_waitcnt vmcnt(0)
	v_fma_f32 v18, v14, v18, v8
	v_add_f32_e32 v11, v11, v21
	v_add_f32_e32 v21, v10, v11
	v_pk_mul_f32 v[10:11], v[16:17], v[110:111]
	s_nop 0
	v_add_f32_e32 v11, v11, v18
	v_add_f32_e32 v10, v10, v11
	v_mul_f32_e32 v11, 0xbfb8aa3b, v21
	v_exp_f32_e32 v11, v11
	s_nop 0
	v_add_f32_e32 v11, 1.0, v11
	v_rcp_f32_e32 v11, v11
	s_nop 0
	v_mul_f32_e32 v11, v21, v11
	v_mul_f32_e32 v18, v10, v11
	v_mov_b32_e32 v11, v6
	v_mov_b32_e32 v6, v17
	v_mov_b32_dpp v27, v109 row_ror:2 row_mask:0xf bank_mask:0xf
	v_mov_b32_dpp v32, v108 row_ror:2 row_mask:0xf bank_mask:0xf
	v_mov_b32_dpp v25, v109 row_ror:1 row_mask:0xf bank_mask:0xf
	v_mov_b32_dpp v31, v108 row_ror:1 row_mask:0xf bank_mask:0xf
	v_cndmask_b32_e64 v23, v22, v27, s[40:41]
	v_cndmask_b32_e64 v22, v24, v32, s[40:41]
	v_cndmask_b32_e64 v21, v25, v19, s[38:39]
	v_cndmask_b32_e64 v20, v31, v20, s[38:39]
	v_pk_fma_f32 v[22:23], v[14:15], v[22:23], v[8:9]
	v_mov_b32_e32 v10, v16
	v_pk_fma_f32 v[16:17], v[6:7], v[20:21], v[22:23]
	v_pk_fma_f32 v[16:17], v[10:11], v[108:109], v[16:17]
	s_nop 0
	v_mul_f32_e32 v19, 0xbfb8aa3b, v17
	v_exp_f32_e32 v19, v19
	s_nop 0
	v_add_f32_e32 v19, 1.0, v19
	v_rcp_f32_e32 v19, v19
	s_nop 0
	v_mul_f32_e32 v17, v17, v19
	v_mul_f32_e32 v16, v16, v17
	s_nop 0
	s_nop 0
	v_mov_b32_dpp v24, v93 row_ror:2 row_mask:0xf bank_mask:0xf
	v_mov_b32_dpp v34, v92 row_ror:2 row_mask:0xf bank_mask:0xf
	v_mov_b32_dpp v19, v93 row_ror:1 row_mask:0xf bank_mask:0xf
	v_mov_b32_dpp v33, v92 row_ror:1 row_mask:0xf bank_mask:0xf
	v_cndmask_b32_e64 v23, v27, v24, s[40:41]
	v_cndmask_b32_e64 v22, v32, v34, s[40:41]
	v_cndmask_b32_e64 v21, v19, v25, s[38:39]
	v_cndmask_b32_e64 v20, v33, v31, s[38:39]
	v_pk_fma_f32 v[22:23], v[14:15], v[22:23], v[8:9]
	v_pk_fma_f32 v[20:21], v[6:7], v[20:21], v[22:23]
	v_pk_fma_f32 v[20:21], v[10:11], v[92:93], v[20:21]
	v_mul_f32_e32 v17, 0xbfb8aa3b, v21
	v_exp_f32_e32 v17, v17
	s_nop 0
	v_add_f32_e32 v17, 1.0, v17
	v_rcp_f32_e32 v17, v17
	s_nop 0
	v_mul_f32_e32 v17, v21, v17
	v_mul_f32_e32 v17, v20, v17
	s_nop 1
	v_mov_b32_dpp v27, v77 row_ror:2 row_mask:0xf bank_mask:0xf
	v_mov_b32_dpp v32, v76 row_ror:2 row_mask:0xf bank_mask:0xf
	v_mov_b32_dpp v25, v77 row_ror:1 row_mask:0xf bank_mask:0xf
	v_mov_b32_dpp v31, v76 row_ror:1 row_mask:0xf bank_mask:0xf
	v_cndmask_b32_e64 v23, v24, v27, s[40:41]
	v_cndmask_b32_e64 v22, v34, v32, s[40:41]
	v_cndmask_b32_e64 v21, v25, v19, s[38:39]
	v_cndmask_b32_e64 v20, v31, v33, s[38:39]
	v_pk_fma_f32 v[22:23], v[14:15], v[22:23], v[8:9]
	v_pk_fma_f32 v[20:21], v[6:7], v[20:21], v[22:23]
	v_pk_fma_f32 v[20:21], v[10:11], v[76:77], v[20:21]
	v_mul_f32_e32 v19, 0xbfb8aa3b, v21
	v_exp_f32_e32 v19, v19
	s_nop 0
	v_add_f32_e32 v19, 1.0, v19
	v_rcp_f32_e32 v19, v19
	s_nop 0
	v_mul_f32_e32 v19, v21, v19
	v_mul_f32_e32 v19, v20, v19
	s_nop 1
	v_mov_b32_dpp v33, v61 row_ror:2 row_mask:0xf bank_mask:0xf
	v_mov_b32_dpp v35, v60 row_ror:2 row_mask:0xf bank_mask:0xf
	v_mov_b32_dpp v24, v61 row_ror:1 row_mask:0xf bank_mask:0xf
	v_mov_b32_dpp v34, v60 row_ror:1 row_mask:0xf bank_mask:0xf
	v_cndmask_b32_e64 v23, v27, v33, s[40:41]
	v_cndmask_b32_e64 v22, v32, v35, s[40:41]
	v_cndmask_b32_e64 v21, v24, v25, s[38:39]
	v_cndmask_b32_e64 v20, v34, v31, s[38:39]
	v_pk_fma_f32 v[22:23], v[14:15], v[22:23], v[8:9]
	v_pk_fma_f32 v[20:21], v[6:7], v[20:21], v[22:23]
	v_pk_fma_f32 v[20:21], v[10:11], v[60:61], v[20:21]
	v_mul_f32_e32 v22, 0xbfb8aa3b, v21
	v_exp_f32_e32 v22, v22
	s_nop 0
	v_add_f32_e32 v22, 1.0, v22
	v_rcp_f32_e32 v22, v22
	s_nop 0
	v_mul_f32_e32 v21, v21, v22
	v_mul_f32_e32 v20, v20, v21
	s_nop 1
	v_mov_b32_dpp v27, v45 row_ror:1 row_mask:0xf bank_mask:0xf
	v_mov_b32_dpp v31, v45 row_ror:2 row_mask:0xf bank_mask:0xf
	v_mov_b32_dpp v36, v44 row_ror:2 row_mask:0xf bank_mask:0xf
	v_mov_b32_dpp v32, v44 row_ror:1 row_mask:0xf bank_mask:0xf
	v_cndmask_b32_e64 v23, v27, v24, s[38:39]
	v_cndmask_b32_e64 v25, v33, v31, s[40:41]
	v_cndmask_b32_e64 v24, v35, v36, s[40:41]
	v_cndmask_b32_e64 v22, v32, v34, s[38:39]
	v_pk_fma_f32 v[24:25], v[14:15], v[24:25], v[8:9]
	s_nop 0
	v_pk_fma_f32 v[22:23], v[6:7], v[22:23], v[24:25]
	v_pk_fma_f32 v[22:23], v[10:11], v[44:45], v[22:23]
	s_nop 0
	v_mul_f32_e32 v21, 0xbfb8aa3b, v23
	v_exp_f32_e32 v21, v21
	s_nop 0
	v_add_f32_e32 v21, 1.0, v21
	v_rcp_f32_e32 v21, v21
	s_nop 0
	v_mul_f32_e32 v21, v23, v21
	v_mul_f32_e32 v24, v22, v21
	s_nop 0
	s_nop 0
	v_mov_b32_dpp v22, v29 row_ror:2 row_mask:0xf bank_mask:0xf
	v_mov_b32_dpp v25, v28 row_ror:2 row_mask:0xf bank_mask:0xf
	v_mov_b32_dpp v21, v29 row_ror:1 row_mask:0xf bank_mask:0xf
	v_mov_b32_dpp v23, v28 row_ror:1 row_mask:0xf bank_mask:0xf
	v_cndmask_b32_e64 v35, v31, v22, s[40:41]
	v_cndmask_b32_e64 v34, v36, v25, s[40:41]
	v_cndmask_b32_e64 v33, v21, v27, s[38:39]
	v_cndmask_b32_e64 v32, v23, v32, s[38:39]
	v_pk_fma_f32 v[34:35], v[14:15], v[34:35], v[8:9]
	v_pk_fma_f32 v[32:33], v[6:7], v[32:33], v[34:35]
	s_nop 0
	v_pk_fma_f32 v[28:29], v[10:11], v[28:29], v[32:33]
	v_mul_f32_e32 v27, 0xbfb8aa3b, v29
	v_exp_f32_e32 v27, v27
	s_nop 0
	v_add_f32_e32 v27, 1.0, v27
	v_rcp_f32_e32 v27, v27
	s_nop 0
	v_mul_f32_e32 v27, v29, v27
	v_mul_f32_e32 v27, v28, v27
	s_nop 0
	s_nop 1
	v_mov_b32_dpp v28, v13 row_ror:1 row_mask:0xf bank_mask:0xf
	v_mov_b32_dpp v29, v13 row_ror:2 row_mask:0xf bank_mask:0xf
	v_mov_b32_dpp v31, v12 row_ror:1 row_mask:0xf bank_mask:0xf
	v_mov_b32_dpp v32, v12 row_ror:2 row_mask:0xf bank_mask:0xf
	v_cmp_gt_i32_e32 vcc, s97, v198
	s_and_b64 s[44:45], s[40:41], vcc
	s_and_saveexec_b64 s[34:35], s[44:45]
	s_cbranch_execz .LBB0_45
	v_cvt_pk_bf16_f32 v37, v39, v18
	v_add_u32_e32 v18, s20, v198
	v_mov_b64_e32 v[44:45], s[8:9]
	s_movk_i32 s21, 0x1600
	v_mad_i64_i32 v[44:45], s[44:45], v18, s21, v[44:45]
	v_cvt_pk_bf16_f32 v34, v184, v137
	v_cvt_pk_bf16_f32 v35, v99, v63
	v_cvt_pk_bf16_f32 v36, v56, v43
	v_lshl_add_u64 v[44:45], v[4:5], 1, v[44:45]
	flat_store_dwordx4 v[44:45], v[34:37]
